# GEMM K-loops: deleted the 30 redundant second lgkmcnt(0) waits that followed s_setprio 1 (first wait already drained LDS)
# speedup vs baseline: 1.0285x; 1.0130x over previous
; #define PG8_STAGE(bufoff, gbase, v0, v1) do { \
;         __builtin_amdgcn_global_load_lds((const unsigned*)((const char*)(gbase) + (v0)), (LAS unsigned*)(lds + (bufoff) + ldsw), 16, 0, 0); \
;         __builtin_amdgcn_global_load_lds((const unsigned*)((const char*)(gbase) + (v1)), (LAS unsigned*)(lds + (bufoff) + ldsw + 8192), 16, 0, 0); } while (0)
; #define PG8_LDA(dst, b, h) do { _Pragma("unroll") for (int m = 0; m < 4; ++m) _Pragma("unroll") for (int k = 0; k < 2; ++k) dst[m][k] = *(const LAS bf16x8*)(lds + PG8_SA(b, h) + aoff + m * 2048 + k * 1024); } while (0)
; #define PG8_LDB(dst, b, h) do { _Pragma("unroll") for (int n = 0; n < 2; ++n) _Pragma("unroll") for (int k = 0; k < 2; ++k) dst[n][k] = *(const LAS bf16x8*)(lds + PG8_SB(b, h) + boff + n * 2048 + k * 1024); } while (0)
; #define PG8_MMA(ai, bj, At, Bt) do { __builtin_amdgcn_s_setprio(1); _Pragma("unroll") for (int m = 0; m < 4; ++m) _Pragma("unroll") for (int n = 0; n < 2; ++n) _Pragma("unroll") for (int k = 0; k < 2; ++k) \
;         acc[ai][bj][m][n] = __builtin_amdgcn_mfma_f32_16x16x32_bf16(Bt[n][k], At[m][k], acc[ai][bj][m][n], 0, 0, 0); __builtin_amdgcn_s_setprio(0); } while (0)
; #define PG8_WAIT_L(n) asm volatile("s_waitcnt lgkmcnt(" #n ")" ::: "memory")
; template <class Epi, class Sched>
; __device__ __forceinline__ void gemm_phase(LAS unsigned char* lds, const Sched& S, const Epi& E) {
;     ...
;             const bool last = (t == nt - 2);
;             const char* a1 = cA + (size_t)(t + 1) * kstep;
;             const char* a2 = last ? nA : cA + (size_t)(t + 2) * kstep; const char* b2 = last ? nB : cB + (size_t)(t + 2) * kstep;
;             const char* a3 = a2 + kstep; const char* b3 = b2 + kstep;
;             const unsigned xA0 = last ? nvA0 : vA0, xA1 = last ? nvA1 : vA1, xB0 = last ? nvB0 : vB0, xB1 = last ? nvB1 : vB1;
;             const size_t xhA = last ? nhA : hA, xhB = last ? nhB : hB;
;             PG8_LDB(B0, 0, 0); PG8_SCHED; PG8_LDA(At, 0, 0); PG8_STAGE(PG8_SA(1, 1), a1 + hA, vA0, vA1);
;             PG8_WAIT_L(8); PG8_BAR; PG8_WAIT_L(0); PG8_MMA(0, 0, At, B0); PG8_BAR; PG8_SCHED;
;             PG8_LDB(B1, 0, 1); PG8_STAGE(PG8_SB(0, 0), b2, xB0, xB1);
;             PG8_BAR; PG8_WAIT_L(0); PG8_MMA(0, 1, At, B1); PG8_BAR;
;             PG8_LDA(At, 0, 1); PG8_STAGE(PG8_SA(0, 0), a2, xA0, xA1);
;             PG8_BAR; PG8_WAIT_L(0); PG8_MMA(1, 0, At, B0); PG8_BAR; PG8_SCHED;
.LBB0_306:
	s_add_u32 s21, s26, 0xfff80080
	s_addc_u32 s69, s27, -1
	s_and_b64 s[40:41], exec, s[40:41]
	s_cselect_b32 s41, s23, s69
	s_cselect_b32 s40, s22, s21
	s_add_i32 s21, 0, 0x10000
	v_add_u32_e32 v138, s21, v153
	ds_read_b128 v[158:161], v138
	ds_read_b128 v[182:185], v138 offset:1024
	ds_read_b128 v[186:189], v138 offset:2048
	ds_read_b128 v[190:193], v138 offset:3072
	v_lshl_add_u64 v[226:227], s[26:27], 0, v[132:133]
	s_add_i32 m0, s48, 0xc000
	ds_read_b128 v[194:197], v154
	ds_read_b128 v[198:201], v154 offset:1024
	ds_read_b128 v[202:205], v154 offset:2048
	ds_read_b128 v[206:209], v154 offset:3072
	ds_read_b128 v[210:213], v154 offset:4096
	ds_read_b128 v[214:217], v154 offset:5120
	ds_read_b128 v[218:221], v154 offset:6144
	ds_read_b128 v[222:225], v154 offset:7168
	global_load_lds_dwordx4 v[226:227], off
	v_lshl_add_u64 v[226:227], s[26:27], 0, v[134:135]
	s_add_i32 m0, s48, 0xe000
	s_nop 0
	global_load_lds_dwordx4 v[226:227], off
	s_waitcnt lgkmcnt(8)
	s_barrier
	s_waitcnt lgkmcnt(0)
	s_setprio 1
	v_mfma_f32_16x16x32_bf16 v[124:127], v[158:161], v[194:197], v[124:127]
	v_mfma_f32_16x16x32_bf16 v[120:123], v[186:189], v[194:197], v[120:123]
	v_mfma_f32_16x16x32_bf16 v[116:119], v[158:161], v[202:205], v[116:119]
	v_mfma_f32_16x16x32_bf16 v[112:115], v[186:189], v[202:205], v[112:115]
	v_mfma_f32_16x16x32_bf16 v[100:103], v[158:161], v[210:213], v[100:103]
	v_mfma_f32_16x16x32_bf16 v[96:99], v[186:189], v[210:213], v[96:99]
	v_mfma_f32_16x16x32_bf16 v[84:87], v[158:161], v[218:221], v[84:87]
	v_mfma_f32_16x16x32_bf16 v[80:83], v[186:189], v[218:221], v[80:83]
	v_mfma_f32_16x16x32_bf16 v[124:127], v[182:185], v[198:201], v[124:127]
	v_mfma_f32_16x16x32_bf16 v[120:123], v[190:193], v[198:201], v[120:123]
	v_mfma_f32_16x16x32_bf16 v[116:119], v[182:185], v[206:209], v[116:119]
	v_mfma_f32_16x16x32_bf16 v[112:115], v[190:193], v[206:209], v[112:115]
	v_mfma_f32_16x16x32_bf16 v[100:103], v[182:185], v[214:217], v[100:103]
	v_mfma_f32_16x16x32_bf16 v[96:99], v[190:193], v[214:217], v[96:99]
	v_mfma_f32_16x16x32_bf16 v[84:87], v[182:185], v[222:225], v[84:87]
	v_mfma_f32_16x16x32_bf16 v[80:83], v[190:193], v[222:225], v[80:83]
	s_setprio 0
	s_barrier
	s_add_i32 s69, 0, 0x14000
	s_add_i32 s21, s21, s43
	v_add_u32_e32 v138, s69, v153
	s_mov_b32 m0, s21
	ds_read_b128 v[226:229], v138
	ds_read_b128 v[230:233], v138 offset:1024
	ds_read_b128 v[234:237], v138 offset:2048
	ds_read_b128 v[238:241], v138 offset:3072
	global_load_lds_dwordx4 v136, s[38:39]
	s_add_i32 m0, s21, 0x2000
	v_mov_b32_e32 v147, v137
	global_load_lds_dwordx4 v146, s[38:39]
	s_barrier
	s_waitcnt lgkmcnt(0)
	v_lshl_add_u64 v[242:243], s[38:39], 0, v[136:137]
	v_lshl_add_u64 v[244:245], s[38:39], 0, v[146:147]
	s_setprio 1
	v_mfma_f32_16x16x32_bf16 v[108:111], v[226:229], v[194:197], v[108:111]
	v_mfma_f32_16x16x32_bf16 v[104:107], v[234:237], v[194:197], v[104:107]
	v_mfma_f32_16x16x32_bf16 v[92:95], v[226:229], v[202:205], v[92:95]
	v_mfma_f32_16x16x32_bf16 v[88:91], v[234:237], v[202:205], v[88:91]
	v_mfma_f32_16x16x32_bf16 v[76:79], v[226:229], v[210:213], v[76:79]
	v_mfma_f32_16x16x32_bf16 v[72:75], v[234:237], v[210:213], v[72:75]
	v_mfma_f32_16x16x32_bf16 v[68:71], v[226:229], v[218:221], v[68:71]
	v_mfma_f32_16x16x32_bf16 v[64:67], v[234:237], v[218:221], v[64:67]
	v_mfma_f32_16x16x32_bf16 v[108:111], v[230:233], v[198:201], v[108:111]
	v_mfma_f32_16x16x32_bf16 v[104:107], v[238:241], v[198:201], v[104:107]
	v_mfma_f32_16x16x32_bf16 v[92:95], v[230:233], v[206:209], v[92:95]
	v_mfma_f32_16x16x32_bf16 v[88:91], v[238:241], v[206:209], v[88:91]
	v_mfma_f32_16x16x32_bf16 v[76:79], v[230:233], v[214:217], v[76:79]
	v_mfma_f32_16x16x32_bf16 v[72:75], v[238:241], v[214:217], v[72:75]
	v_mfma_f32_16x16x32_bf16 v[68:71], v[230:233], v[222:225], v[68:71]
	v_mfma_f32_16x16x32_bf16 v[64:67], v[238:241], v[222:225], v[64:67]
	s_setprio 0
	s_mov_b32 m0, s48
	v_lshl_add_u64 v[246:247], s[40:41], 0, v[150:151]
	s_barrier
	ds_read_b128 v[194:197], v154 offset:16384
	ds_read_b128 v[198:201], v154 offset:17408
	ds_read_b128 v[202:205], v154 offset:18432
	ds_read_b128 v[206:209], v154 offset:19456
	ds_read_b128 v[210:213], v154 offset:20480
	ds_read_b128 v[214:217], v154 offset:21504
	ds_read_b128 v[218:221], v154 offset:22528
	ds_read_b128 v[222:225], v154 offset:23552
	global_load_lds_dwordx4 v[246:247], off
	v_lshl_add_u64 v[248:249], s[40:41], 0, v[148:149]
	s_mov_b32 m0, s49
	s_nop 0
	global_load_lds_dwordx4 v[248:249], off
	s_barrier
	s_waitcnt lgkmcnt(0)
	s_setprio 1
	v_mfma_f32_16x16x32_bf16 v[60:63], v[158:161], v[194:197], v[60:63]
	v_mfma_f32_16x16x32_bf16 v[56:59], v[186:189], v[194:197], v[56:59]
	v_mfma_f32_16x16x32_bf16 v[52:55], v[158:161], v[202:205], v[52:55]
	v_mfma_f32_16x16x32_bf16 v[44:47], v[186:189], v[202:205], v[44:47]
	v_mfma_f32_16x16x32_bf16 v[36:39], v[158:161], v[210:213], v[36:39]
	v_mfma_f32_16x16x32_bf16 v[28:31], v[186:189], v[210:213], v[28:31]
	v_mfma_f32_16x16x32_bf16 v[20:23], v[158:161], v[218:221], v[20:23]
	v_mfma_f32_16x16x32_bf16 v[12:15], v[186:189], v[218:221], v[12:15]
	v_mfma_f32_16x16x32_bf16 v[60:63], v[182:185], v[198:201], v[60:63]
	v_mfma_f32_16x16x32_bf16 v[56:59], v[190:193], v[198:201], v[56:59]
	v_mfma_f32_16x16x32_bf16 v[52:55], v[182:185], v[206:209], v[52:55]
	v_mfma_f32_16x16x32_bf16 v[44:47], v[190:193], v[206:209], v[44:47]
	v_mfma_f32_16x16x32_bf16 v[36:39], v[182:185], v[214:217], v[36:39]
	v_mfma_f32_16x16x32_bf16 v[28:31], v[190:193], v[214:217], v[28:31]
	v_mfma_f32_16x16x32_bf16 v[20:23], v[182:185], v[222:225], v[20:23]
	v_mfma_f32_16x16x32_bf16 v[12:15], v[190:193], v[222:225], v[12:15]
	s_setprio 0
	s_barrier
; #define PG8_STAGE(bufoff, gbase, v0, v1) do { \
;         __builtin_amdgcn_global_load_lds((const unsigned*)((const char*)(gbase) + (v0)), (LAS unsigned*)(lds + (bufoff) + ldsw), 16, 0, 0); \
;         __builtin_amdgcn_global_load_lds((const unsigned*)((const char*)(gbase) + (v1)), (LAS unsigned*)(lds + (bufoff) + ldsw + 8192), 16, 0, 0); } while (0)
; #define PG8_LDA(dst, b, h) do { _Pragma("unroll") for (int m = 0; m < 4; ++m) _Pragma("unroll") for (int k = 0; k < 2; ++k) dst[m][k] = *(const LAS bf16x8*)(lds + PG8_SA(b, h) + aoff + m * 2048 + k * 1024); } while (0)
; #define PG8_LDB(dst, b, h) do { _Pragma("unroll") for (int n = 0; n < 2; ++n) _Pragma("unroll") for (int k = 0; k < 2; ++k) dst[n][k] = *(const LAS bf16x8*)(lds + PG8_SB(b, h) + boff + n * 2048 + k * 1024); } while (0)
; #define PG8_MMA(ai, bj, At, Bt) do { __builtin_amdgcn_s_setprio(1); _Pragma("unroll") for (int m = 0; m < 4; ++m) _Pragma("unroll") for (int n = 0; n < 2; ++n) _Pragma("unroll") for (int k = 0; k < 2; ++k) \
;         acc[ai][bj][m][n] = __builtin_amdgcn_mfma_f32_16x16x32_bf16(Bt[n][k], At[m][k], acc[ai][bj][m][n], 0, 0, 0); __builtin_amdgcn_s_setprio(0); } while (0)
; #define PG8_WAIT_V(n) asm volatile("s_waitcnt vmcnt(" #n ")" ::: "memory")
; #define PG8_WAIT_L(n) asm volatile("s_waitcnt lgkmcnt(" #n ")" ::: "memory")
; #define PG8_BAR __builtin_amdgcn_s_barrier()
; #define PG8_SCHED __builtin_amdgcn_sched_barrier(0)
; template <class Epi, class Sched>
; __device__ __forceinline__ void gemm_phase(LAS unsigned char* lds, const Sched& S, const Epi& E) {
;     ...
;             PG8_STAGE(PG8_SB(0, 1), b2 + xhB, xB0, xB1);
;             PG8_WAIT_V(6); PG8_BAR; PG8_MMA(1, 1, At, B1); PG8_BAR;
;             PG8_LDB(B0, 1, 0); PG8_SCHED; PG8_LDA(At, 1, 0); PG8_STAGE(PG8_SA(0, 1), a2 + xhA, xA0, xA1);
;             PG8_WAIT_L(8); PG8_BAR; PG8_WAIT_L(0); PG8_MMA(0, 0, At, B0); PG8_BAR; PG8_SCHED;
;             PG8_LDB(B1, 1, 1); PG8_STAGE(PG8_SB(1, 0), b3, xB0, xB1);
	s_add_u32 s70, s38, 0x80000
	s_addc_u32 s71, s39, 0
	s_add_i32 s21, s69, s43
	s_mov_b32 m0, s21
	s_nop 0
	global_load_lds_dwordx4 v136, s[70:71]
	s_add_i32 m0, s21, 0x2000
	s_nop 0
	global_load_lds_dwordx4 v146, s[70:71]
	s_waitcnt vmcnt(6)
	s_barrier
	s_setprio 1
	v_mfma_f32_16x16x32_bf16 v[48:51], v[226:229], v[194:197], v[48:51]
	v_mfma_f32_16x16x32_bf16 v[40:43], v[234:237], v[194:197], v[40:43]
	v_mfma_f32_16x16x32_bf16 v[32:35], v[226:229], v[202:205], v[32:35]
	v_mfma_f32_16x16x32_bf16 v[24:27], v[234:237], v[202:205], v[24:27]
	v_mfma_f32_16x16x32_bf16 v[16:19], v[226:229], v[210:213], v[16:19]
	v_mfma_f32_16x16x32_bf16 v[8:11], v[234:237], v[210:213], v[8:11]
	v_mfma_f32_16x16x32_bf16 v[4:7], v[226:229], v[218:221], v[4:7]
	v_mfma_f32_16x16x32_bf16 v[0:3], v[234:237], v[218:221], v[0:3]
	v_mfma_f32_16x16x32_bf16 v[48:51], v[230:233], v[198:201], v[48:51]
	v_mfma_f32_16x16x32_bf16 v[40:43], v[238:241], v[198:201], v[40:43]
	v_mfma_f32_16x16x32_bf16 v[32:35], v[230:233], v[206:209], v[32:35]
	v_mfma_f32_16x16x32_bf16 v[24:27], v[238:241], v[206:209], v[24:27]
	v_mfma_f32_16x16x32_bf16 v[16:19], v[230:233], v[214:217], v[16:19]
	v_mfma_f32_16x16x32_bf16 v[8:11], v[238:241], v[214:217], v[8:11]
	v_mfma_f32_16x16x32_bf16 v[4:7], v[230:233], v[222:225], v[4:7]
	v_mfma_f32_16x16x32_bf16 v[0:3], v[238:241], v[222:225], v[0:3]
	s_setprio 0
	s_add_i32 s21, 0, 0x18000
	v_add_u32_e32 v138, s21, v153
	s_barrier
	ds_read_b128 v[158:161], v138
	ds_read_b128 v[182:185], v138 offset:1024
	ds_read_b128 v[186:189], v138 offset:2048
	ds_read_b128 v[190:193], v138 offset:3072
	s_add_u32 s40, s40, 0x80000
	s_addc_u32 s41, s41, 0
	s_mov_b32 m0, s50
	v_lshl_add_u64 v[150:151], s[40:41], 0, v[150:151]
	ds_read_b128 v[194:197], v154 offset:32768
	ds_read_b128 v[198:201], v154 offset:33792
	ds_read_b128 v[202:205], v154 offset:34816
	ds_read_b128 v[206:209], v154 offset:35840
	ds_read_b128 v[210:213], v154 offset:36864
	ds_read_b128 v[214:217], v154 offset:37888
	ds_read_b128 v[218:221], v154 offset:38912
	ds_read_b128 v[222:225], v154 offset:39936
	global_load_lds_dwordx4 v[150:151], off
	v_lshl_add_u64 v[148:149], s[40:41], 0, v[148:149]
	s_mov_b32 m0, s51
	s_nop 0
	global_load_lds_dwordx4 v[148:149], off
	s_waitcnt lgkmcnt(8)
	s_barrier
	s_waitcnt lgkmcnt(0)
	s_setprio 1
	v_mfma_f32_16x16x32_bf16 v[124:127], v[158:161], v[194:197], v[124:127]
	v_mfma_f32_16x16x32_bf16 v[120:123], v[186:189], v[194:197], v[120:123]
	v_mfma_f32_16x16x32_bf16 v[116:119], v[158:161], v[202:205], v[116:119]
	v_mfma_f32_16x16x32_bf16 v[112:115], v[186:189], v[202:205], v[112:115]
	v_mfma_f32_16x16x32_bf16 v[100:103], v[158:161], v[210:213], v[100:103]
	v_mfma_f32_16x16x32_bf16 v[96:99], v[186:189], v[210:213], v[96:99]
	v_mfma_f32_16x16x32_bf16 v[84:87], v[158:161], v[218:221], v[84:87]
	v_mfma_f32_16x16x32_bf16 v[80:83], v[186:189], v[218:221], v[80:83]
	v_mfma_f32_16x16x32_bf16 v[124:127], v[182:185], v[198:201], v[124:127]
	v_mfma_f32_16x16x32_bf16 v[120:123], v[190:193], v[198:201], v[120:123]
	v_mfma_f32_16x16x32_bf16 v[116:119], v[182:185], v[206:209], v[116:119]
	v_mfma_f32_16x16x32_bf16 v[112:115], v[190:193], v[206:209], v[112:115]
	v_mfma_f32_16x16x32_bf16 v[100:103], v[182:185], v[214:217], v[100:103]
	v_mfma_f32_16x16x32_bf16 v[96:99], v[190:193], v[214:217], v[96:99]
	v_mfma_f32_16x16x32_bf16 v[84:87], v[182:185], v[222:225], v[84:87]
	v_mfma_f32_16x16x32_bf16 v[80:83], v[190:193], v[222:225], v[80:83]
	s_setprio 0
	s_barrier
	s_add_i32 s40, 0, 0x1c000
	s_add_i32 s21, s21, s43
	v_add_u32_e32 v138, s40, v153
	v_lshl_add_u64 v[238:239], v[242:243], 0, s[44:45]
	s_mov_b32 m0, s21
	ds_read_b128 v[148:151], v138
	ds_read_b128 v[226:229], v138 offset:1024
	ds_read_b128 v[230:233], v138 offset:2048
	ds_read_b128 v[234:237], v138 offset:3072
	global_load_lds_dwordx4 v[238:239], off
	v_lshl_add_u64 v[238:239], v[244:245], 0, s[44:45]
	s_add_i32 m0, s21, 0x2000
	s_nop 0
	global_load_lds_dwordx4 v[238:239], off
	s_barrier
; #define PG8_STAGE(bufoff, gbase, v0, v1) do { \
;         __builtin_amdgcn_global_load_lds((const unsigned*)((const char*)(gbase) + (v0)), (LAS unsigned*)(lds + (bufoff) + ldsw), 16, 0, 0); \
;         __builtin_amdgcn_global_load_lds((const unsigned*)((const char*)(gbase) + (v1)), (LAS unsigned*)(lds + (bufoff) + ldsw + 8192), 16, 0, 0); } while (0)
; #define PG8_LDA(dst, b, h) do { _Pragma("unroll") for (int m = 0; m < 4; ++m) _Pragma("unroll") for (int k = 0; k < 2; ++k) dst[m][k] = *(const LAS bf16x8*)(lds + PG8_SA(b, h) + aoff + m * 2048 + k * 1024); } while (0)
; #define PG8_MMA(ai, bj, At, Bt) do { __builtin_amdgcn_s_setprio(1); _Pragma("unroll") for (int m = 0; m < 4; ++m) _Pragma("unroll") for (int n = 0; n < 2; ++n) _Pragma("unroll") for (int k = 0; k < 2; ++k) \
;         acc[ai][bj][m][n] = __builtin_amdgcn_mfma_f32_16x16x32_bf16(Bt[n][k], At[m][k], acc[ai][bj][m][n], 0, 0, 0); __builtin_amdgcn_s_setprio(0); } while (0)
; #define PG8_WAIT_V(n) asm volatile("s_waitcnt vmcnt(" #n ")" ::: "memory")
; #define PG8_WAIT_L(n) asm volatile("s_waitcnt lgkmcnt(" #n ")" ::: "memory")
; #define PG8_BAR __builtin_amdgcn_s_barrier()
; #define PG8_SCHED __builtin_amdgcn_sched_barrier(0)
; template <class Epi, class Sched>
; __device__ __forceinline__ void gemm_phase(LAS unsigned char* lds, const Sched& S, const Epi& E) {
;     ...
;             const bool last = (t == nt - 2);
;             const char* a1 = cA + (size_t)(t + 1) * kstep;
;             const char* a2 = last ? nA : cA + (size_t)(t + 2) * kstep; const char* b2 = last ? nB : cB + (size_t)(t + 2) * kstep;
;             const char* a3 = a2 + kstep; const char* b3 = b2 + kstep;
;             const unsigned xA0 = last ? nvA0 : vA0, xA1 = last ? nvA1 : vA1, xB0 = last ? nvB0 : vB0, xB1 = last ? nvB1 : vB1;
;             const size_t xhA = last ? nhA : hA, xhB = last ? nhB : hB;
;     ...
;             PG8_BAR; PG8_WAIT_L(0); PG8_MMA(0, 1, At, B1); PG8_BAR;
;             PG8_LDA(At, 1, 1); PG8_STAGE(PG8_SA(1, 0), a3, xA0, xA1);
;             PG8_BAR; PG8_WAIT_L(0); PG8_MMA(1, 0, At, B0); PG8_BAR; PG8_SCHED;
;             PG8_STAGE(PG8_SB(1, 1), b3 + xhB, xB0, xB1);
;             PG8_WAIT_V(6); PG8_BAR; PG8_MMA(1, 1, At, B1); PG8_BAR;
	s_waitcnt lgkmcnt(0)
	s_setprio 1
	v_mfma_f32_16x16x32_bf16 v[108:111], v[148:151], v[194:197], v[108:111]
	v_mfma_f32_16x16x32_bf16 v[104:107], v[230:233], v[194:197], v[104:107]
	v_mfma_f32_16x16x32_bf16 v[92:95], v[148:151], v[202:205], v[92:95]
	v_mfma_f32_16x16x32_bf16 v[88:91], v[230:233], v[202:205], v[88:91]
	v_mfma_f32_16x16x32_bf16 v[76:79], v[148:151], v[210:213], v[76:79]
	v_mfma_f32_16x16x32_bf16 v[72:75], v[230:233], v[210:213], v[72:75]
	v_mfma_f32_16x16x32_bf16 v[68:71], v[148:151], v[218:221], v[68:71]
	v_mfma_f32_16x16x32_bf16 v[64:67], v[230:233], v[218:221], v[64:67]
	v_mfma_f32_16x16x32_bf16 v[108:111], v[226:229], v[198:201], v[108:111]
	v_mfma_f32_16x16x32_bf16 v[104:107], v[234:237], v[198:201], v[104:107]
	v_mfma_f32_16x16x32_bf16 v[92:95], v[226:229], v[206:209], v[92:95]
	v_mfma_f32_16x16x32_bf16 v[88:91], v[234:237], v[206:209], v[88:91]
	v_mfma_f32_16x16x32_bf16 v[76:79], v[226:229], v[214:217], v[76:79]
	v_mfma_f32_16x16x32_bf16 v[72:75], v[234:237], v[214:217], v[72:75]
	v_mfma_f32_16x16x32_bf16 v[68:71], v[226:229], v[222:225], v[68:71]
	v_mfma_f32_16x16x32_bf16 v[64:67], v[234:237], v[222:225], v[64:67]
	s_setprio 0
	s_mov_b32 m0, s64
	v_lshl_add_u64 v[238:239], v[246:247], 0, s[44:45]
	s_barrier
	ds_read_b128 v[194:197], v154 offset:49152
	ds_read_b128 v[198:201], v154 offset:50176
	ds_read_b128 v[202:205], v154 offset:51200
	ds_read_b128 v[206:209], v154 offset:52224
	ds_read_b128 v[210:213], v154 offset:53248
	ds_read_b128 v[214:217], v154 offset:54272
	ds_read_b128 v[218:221], v154 offset:55296
	ds_read_b128 v[222:225], v154 offset:56320
	global_load_lds_dwordx4 v[238:239], off
	v_lshl_add_u64 v[238:239], v[248:249], 0, s[44:45]
	s_mov_b32 m0, s65
	s_nop 0
	global_load_lds_dwordx4 v[238:239], off
	s_barrier
	s_waitcnt lgkmcnt(0)
	s_setprio 1
	v_mfma_f32_16x16x32_bf16 v[60:63], v[158:161], v[194:197], v[60:63]
	v_mfma_f32_16x16x32_bf16 v[56:59], v[186:189], v[194:197], v[56:59]
	v_mfma_f32_16x16x32_bf16 v[52:55], v[158:161], v[202:205], v[52:55]
	v_mfma_f32_16x16x32_bf16 v[44:47], v[186:189], v[202:205], v[44:47]
	v_mfma_f32_16x16x32_bf16 v[36:39], v[158:161], v[210:213], v[36:39]
	v_mfma_f32_16x16x32_bf16 v[28:31], v[186:189], v[210:213], v[28:31]
	v_mfma_f32_16x16x32_bf16 v[20:23], v[158:161], v[218:221], v[20:23]
	v_mfma_f32_16x16x32_bf16 v[12:15], v[186:189], v[218:221], v[12:15]
	v_mfma_f32_16x16x32_bf16 v[60:63], v[182:185], v[198:201], v[60:63]
	v_mfma_f32_16x16x32_bf16 v[56:59], v[190:193], v[198:201], v[56:59]
	v_mfma_f32_16x16x32_bf16 v[52:55], v[182:185], v[206:209], v[52:55]
	v_mfma_f32_16x16x32_bf16 v[44:47], v[190:193], v[206:209], v[44:47]
	v_mfma_f32_16x16x32_bf16 v[36:39], v[182:185], v[214:217], v[36:39]
	v_mfma_f32_16x16x32_bf16 v[28:31], v[190:193], v[214:217], v[28:31]
	v_mfma_f32_16x16x32_bf16 v[20:23], v[182:185], v[222:225], v[20:23]
	v_mfma_f32_16x16x32_bf16 v[12:15], v[190:193], v[222:225], v[12:15]
	s_setprio 0
	s_barrier
	s_add_u32 s38, s38, 0x80080
	s_addc_u32 s39, s39, 0
	s_add_i32 s21, s40, s43
	s_mov_b32 m0, s21
	s_nop 0
	global_load_lds_dwordx4 v136, s[38:39]
	s_add_i32 m0, s21, 0x2000
	s_nop 0
	global_load_lds_dwordx4 v146, s[38:39]
	s_waitcnt vmcnt(6)
	s_barrier
	s_setprio 1
	v_mfma_f32_16x16x32_bf16 v[48:51], v[148:151], v[194:197], v[48:51]
	v_mfma_f32_16x16x32_bf16 v[40:43], v[230:233], v[194:197], v[40:43]
	v_mfma_f32_16x16x32_bf16 v[32:35], v[148:151], v[202:205], v[32:35]
	v_mfma_f32_16x16x32_bf16 v[24:27], v[230:233], v[202:205], v[24:27]
	v_mfma_f32_16x16x32_bf16 v[16:19], v[148:151], v[210:213], v[16:19]
	v_mfma_f32_16x16x32_bf16 v[8:11], v[230:233], v[210:213], v[8:11]
	v_mfma_f32_16x16x32_bf16 v[4:7], v[148:151], v[218:221], v[4:7]
	v_mfma_f32_16x16x32_bf16 v[0:3], v[230:233], v[218:221], v[0:3]
	v_mfma_f32_16x16x32_bf16 v[48:51], v[226:229], v[198:201], v[48:51]
	v_mfma_f32_16x16x32_bf16 v[40:43], v[234:237], v[198:201], v[40:43]
	v_mfma_f32_16x16x32_bf16 v[32:35], v[226:229], v[206:209], v[32:35]
	v_mfma_f32_16x16x32_bf16 v[24:27], v[234:237], v[206:209], v[24:27]
	v_mfma_f32_16x16x32_bf16 v[16:19], v[226:229], v[214:217], v[16:19]
	v_mfma_f32_16x16x32_bf16 v[8:11], v[234:237], v[214:217], v[8:11]
	v_mfma_f32_16x16x32_bf16 v[4:7], v[226:229], v[222:225], v[4:7]
	v_mfma_f32_16x16x32_bf16 v[0:3], v[234:237], v[222:225], v[0:3]
	s_setprio 0
	s_add_i32 s15, s15, 2
	s_add_u32 s26, s26, 0x100
	s_addc_u32 s27, s27, 0
	s_add_u32 s34, s34, 0x100
	s_addc_u32 s35, s35, 0
	s_cmp_gt_u32 s15, 29
	s_cbranch_scc1 .Lrot_exit_0
	s_cmp_eq_u32 s15, 28
	s_cselect_b64 s[40:41], -1, 0
	s_and_b64 vcc, exec, s[40:41]
	v_mov_b64_e32 v[148:149], v[130:131]
	v_mov_b64_e32 v[150:151], v[128:129]
	v_mov_b32_e32 v146, v156
	v_mov_b32_e32 v136, v155
	s_mov_b64 s[38:39], s[24:25]
	s_cbranch_vccnz .Lrot_join_0
	v_mov_b64_e32 v[148:149], v[134:135]
	v_mov_b64_e32 v[150:151], v[132:133]
	v_mov_b32_e32 v146, v142
	v_mov_b32_e32 v136, v144
	s_mov_b64 s[38:39], s[34:35]

; #define PG8_STAGE(bufoff, gbase, v0, v1) do { \
;         __builtin_amdgcn_global_load_lds((const unsigned*)((const char*)(gbase) + (v0)), (LAS unsigned*)(lds + (bufoff) + ldsw), 16, 0, 0); \
;         __builtin_amdgcn_global_load_lds((const unsigned*)((const char*)(gbase) + (v1)), (LAS unsigned*)(lds + (bufoff) + ldsw + 8192), 16, 0, 0); } while (0)
; #define PG8_LDA(dst, b, h) do { _Pragma("unroll") for (int m = 0; m < 4; ++m) _Pragma("unroll") for (int k = 0; k < 2; ++k) dst[m][k] = *(const LAS bf16x8*)(lds + PG8_SA(b, h) + aoff + m * 2048 + k * 1024); } while (0)
; #define PG8_LDB(dst, b, h) do { _Pragma("unroll") for (int n = 0; n < 2; ++n) _Pragma("unroll") for (int k = 0; k < 2; ++k) dst[n][k] = *(const LAS bf16x8*)(lds + PG8_SB(b, h) + boff + n * 2048 + k * 1024); } while (0)
; #define PG8_MMA(ai, bj, At, Bt) do { __builtin_amdgcn_s_setprio(1); _Pragma("unroll") for (int m = 0; m < 4; ++m) _Pragma("unroll") for (int n = 0; n < 2; ++n) _Pragma("unroll") for (int k = 0; k < 2; ++k) \
;         acc[ai][bj][m][n] = __builtin_amdgcn_mfma_f32_16x16x32_bf16(Bt[n][k], At[m][k], acc[ai][bj][m][n], 0, 0, 0); __builtin_amdgcn_s_setprio(0); } while (0)
; #define PG8_WAIT_L(n) asm volatile("s_waitcnt lgkmcnt(" #n ")" ::: "memory")
; template <class Epi, class Sched>
; __device__ __forceinline__ void gemm_phase(LAS unsigned char* lds, const Sched& S, const Epi& E) {
;     ...
;             const bool last = (t == nt - 2);
;             const char* a1 = cA + (size_t)(t + 1) * kstep;
;             const char* a2 = last ? nA : cA + (size_t)(t + 2) * kstep; const char* b2 = last ? nB : cB + (size_t)(t + 2) * kstep;
;             const char* a3 = a2 + kstep; const char* b3 = b2 + kstep;
;             const unsigned xA0 = last ? nvA0 : vA0, xA1 = last ? nvA1 : vA1, xB0 = last ? nvB0 : vB0, xB1 = last ? nvB1 : vB1;
;             const size_t xhA = last ? nhA : hA, xhB = last ? nhB : hB;
;             PG8_LDB(B0, 0, 0); PG8_SCHED; PG8_LDA(At, 0, 0); PG8_STAGE(PG8_SA(1, 1), a1 + hA, vA0, vA1);
;             PG8_WAIT_L(8); PG8_BAR; PG8_WAIT_L(0); PG8_MMA(0, 0, At, B0); PG8_BAR; PG8_SCHED;
;             PG8_LDB(B1, 0, 1); PG8_STAGE(PG8_SB(0, 0), b2, xB0, xB1);
;             PG8_BAR; PG8_WAIT_L(0); PG8_MMA(0, 1, At, B1); PG8_BAR;
;             PG8_LDA(At, 0, 1); PG8_STAGE(PG8_SA(0, 0), a2, xA0, xA1);
;             PG8_BAR; PG8_WAIT_L(0); PG8_MMA(1, 0, At, B0); PG8_BAR; PG8_SCHED;
.LBB0_574:
	s_add_i32 s49, s49, 2
	s_add_u32 s65, s34, 0x80
	s_addc_u32 vcc_lo, s35, 0
	s_and_b64 s[54:55], exec, s[54:55]
	s_cselect_b32 s55, s41, vcc_lo
	s_cselect_b32 s54, s40, s65
	s_add_i32 s65, 0, 0x10000
	v_add_u32_e32 v138, s65, v184
	ds_read_b128 v[158:161], v138
	ds_read_b128 v[186:189], v138 offset:1024
	ds_read_b128 v[190:193], v138 offset:2048
	ds_read_b128 v[194:197], v138 offset:3072
	v_lshl_add_u64 v[230:231], s[34:35], 0, v[134:135]
	s_add_i32 m0, s91, 0xc000
	ds_read_b128 v[198:201], v185
	ds_read_b128 v[202:205], v185 offset:1024
	ds_read_b128 v[206:209], v185 offset:2048
	ds_read_b128 v[210:213], v185 offset:3072
	ds_read_b128 v[214:217], v185 offset:4096
	ds_read_b128 v[218:221], v185 offset:5120
	ds_read_b128 v[222:225], v185 offset:6144
	ds_read_b128 v[226:229], v185 offset:7168
	global_load_lds_dwordx4 v[230:231], off
	v_lshl_add_u64 v[230:231], s[34:35], 0, v[150:151]
	s_add_i32 m0, s91, 0xe000
	s_nop 0
	global_load_lds_dwordx4 v[230:231], off
	s_waitcnt lgkmcnt(8)
	s_barrier
	s_waitcnt lgkmcnt(0)
	s_setprio 1
	v_mfma_f32_16x16x32_bf16 v[124:127], v[158:161], v[198:201], v[124:127]
	v_mfma_f32_16x16x32_bf16 v[120:123], v[190:193], v[198:201], v[120:123]
	v_mfma_f32_16x16x32_bf16 v[116:119], v[158:161], v[206:209], v[116:119]
	v_mfma_f32_16x16x32_bf16 v[112:115], v[190:193], v[206:209], v[112:115]
	v_mfma_f32_16x16x32_bf16 v[108:111], v[158:161], v[214:217], v[108:111]
	v_mfma_f32_16x16x32_bf16 v[104:107], v[190:193], v[214:217], v[104:107]
	v_mfma_f32_16x16x32_bf16 v[100:103], v[158:161], v[222:225], v[100:103]
	v_mfma_f32_16x16x32_bf16 v[96:99], v[190:193], v[222:225], v[96:99]
	v_mfma_f32_16x16x32_bf16 v[124:127], v[186:189], v[202:205], v[124:127]
	v_mfma_f32_16x16x32_bf16 v[120:123], v[194:197], v[202:205], v[120:123]
	v_mfma_f32_16x16x32_bf16 v[116:119], v[186:189], v[210:213], v[116:119]
	v_mfma_f32_16x16x32_bf16 v[112:115], v[194:197], v[210:213], v[112:115]
	v_mfma_f32_16x16x32_bf16 v[108:111], v[186:189], v[218:221], v[108:111]
	v_mfma_f32_16x16x32_bf16 v[104:107], v[194:197], v[218:221], v[104:107]
	v_mfma_f32_16x16x32_bf16 v[100:103], v[186:189], v[226:229], v[100:103]
	v_mfma_f32_16x16x32_bf16 v[96:99], v[194:197], v[226:229], v[96:99]
	s_setprio 0
	s_barrier
	s_add_i32 vcc_lo, 0, 0x14000
	s_add_i32 s65, s65, s9
	v_add_u32_e32 v138, vcc_lo, v184
	s_mov_b32 m0, s65
	ds_read_b128 v[230:233], v138
	ds_read_b128 v[234:237], v138 offset:1024
	ds_read_b128 v[238:241], v138 offset:2048
	ds_read_b128 v[242:245], v138 offset:3072
	global_load_lds_dwordx4 v136, s[92:93]
	s_add_i32 m0, s65, 0x2000
	v_mov_b32_e32 v157, v137
	global_load_lds_dwordx4 v156, s[92:93]
	s_barrier
	s_waitcnt lgkmcnt(0)
	v_lshl_add_u64 v[246:247], s[92:93], 0, v[136:137]
	v_lshl_add_u64 v[248:249], s[92:93], 0, v[156:157]
	s_setprio 1
	v_mfma_f32_16x16x32_bf16 v[92:95], v[230:233], v[198:201], v[92:95]
	v_mfma_f32_16x16x32_bf16 v[88:91], v[238:241], v[198:201], v[88:91]
	v_mfma_f32_16x16x32_bf16 v[84:87], v[230:233], v[206:209], v[84:87]
	v_mfma_f32_16x16x32_bf16 v[80:83], v[238:241], v[206:209], v[80:83]
	v_mfma_f32_16x16x32_bf16 v[76:79], v[230:233], v[214:217], v[76:79]
	v_mfma_f32_16x16x32_bf16 v[72:75], v[238:241], v[214:217], v[72:75]
	v_mfma_f32_16x16x32_bf16 v[68:71], v[230:233], v[222:225], v[68:71]
	v_mfma_f32_16x16x32_bf16 v[64:67], v[238:241], v[222:225], v[64:67]
	v_mfma_f32_16x16x32_bf16 v[92:95], v[234:237], v[202:205], v[92:95]
	v_mfma_f32_16x16x32_bf16 v[88:91], v[242:245], v[202:205], v[88:91]
	v_mfma_f32_16x16x32_bf16 v[84:87], v[234:237], v[210:213], v[84:87]
	v_mfma_f32_16x16x32_bf16 v[80:83], v[242:245], v[210:213], v[80:83]
	v_mfma_f32_16x16x32_bf16 v[76:79], v[234:237], v[218:221], v[76:79]
	v_mfma_f32_16x16x32_bf16 v[72:75], v[242:245], v[218:221], v[72:75]
	v_mfma_f32_16x16x32_bf16 v[68:71], v[234:237], v[226:229], v[68:71]
	v_mfma_f32_16x16x32_bf16 v[64:67], v[242:245], v[226:229], v[64:67]
	s_setprio 0
	s_mov_b32 m0, s91
	v_lshl_add_u64 v[250:251], s[54:55], 0, v[154:155]
	s_barrier
	ds_read_b128 v[198:201], v185 offset:16384
	ds_read_b128 v[202:205], v185 offset:17408
	ds_read_b128 v[206:209], v185 offset:18432
	ds_read_b128 v[210:213], v185 offset:19456
	ds_read_b128 v[214:217], v185 offset:20480
	ds_read_b128 v[218:221], v185 offset:21504
	ds_read_b128 v[222:225], v185 offset:22528
	ds_read_b128 v[226:229], v185 offset:23552
	global_load_lds_dwordx4 v[250:251], off
	v_lshl_add_u64 v[140:141], s[54:55], 0, v[152:153]
	s_mov_b32 m0, s50
	s_nop 0
	global_load_lds_dwordx4 v[140:141], off
	s_barrier
	s_waitcnt lgkmcnt(0)
	s_setprio 1
	v_mfma_f32_16x16x32_bf16 v[60:63], v[158:161], v[198:201], v[60:63]
	v_mfma_f32_16x16x32_bf16 v[56:59], v[190:193], v[198:201], v[56:59]
	v_mfma_f32_16x16x32_bf16 v[52:55], v[158:161], v[206:209], v[52:55]
	v_mfma_f32_16x16x32_bf16 v[48:51], v[190:193], v[206:209], v[48:51]
	v_mfma_f32_16x16x32_bf16 v[44:47], v[158:161], v[214:217], v[44:47]
	v_mfma_f32_16x16x32_bf16 v[40:43], v[190:193], v[214:217], v[40:43]
	v_mfma_f32_16x16x32_bf16 v[36:39], v[158:161], v[222:225], v[36:39]
	v_mfma_f32_16x16x32_bf16 v[32:35], v[190:193], v[222:225], v[32:35]
	v_mfma_f32_16x16x32_bf16 v[60:63], v[186:189], v[202:205], v[60:63]
	v_mfma_f32_16x16x32_bf16 v[56:59], v[194:197], v[202:205], v[56:59]
	v_mfma_f32_16x16x32_bf16 v[52:55], v[186:189], v[210:213], v[52:55]
	v_mfma_f32_16x16x32_bf16 v[48:51], v[194:197], v[210:213], v[48:51]
	v_mfma_f32_16x16x32_bf16 v[44:47], v[186:189], v[218:221], v[44:47]
	v_mfma_f32_16x16x32_bf16 v[40:43], v[194:197], v[218:221], v[40:43]
	v_mfma_f32_16x16x32_bf16 v[36:39], v[186:189], v[226:229], v[36:39]
	v_mfma_f32_16x16x32_bf16 v[32:35], v[194:197], v[226:229], v[32:35]
	s_setprio 0
	s_barrier
; #define PG8_STAGE(bufoff, gbase, v0, v1) do { \
;         __builtin_amdgcn_global_load_lds((const unsigned*)((const char*)(gbase) + (v0)), (LAS unsigned*)(lds + (bufoff) + ldsw), 16, 0, 0); \
;         __builtin_amdgcn_global_load_lds((const unsigned*)((const char*)(gbase) + (v1)), (LAS unsigned*)(lds + (bufoff) + ldsw + 8192), 16, 0, 0); } while (0)
; #define PG8_LDA(dst, b, h) do { _Pragma("unroll") for (int m = 0; m < 4; ++m) _Pragma("unroll") for (int k = 0; k < 2; ++k) dst[m][k] = *(const LAS bf16x8*)(lds + PG8_SA(b, h) + aoff + m * 2048 + k * 1024); } while (0)
; #define PG8_LDB(dst, b, h) do { _Pragma("unroll") for (int n = 0; n < 2; ++n) _Pragma("unroll") for (int k = 0; k < 2; ++k) dst[n][k] = *(const LAS bf16x8*)(lds + PG8_SB(b, h) + boff + n * 2048 + k * 1024); } while (0)
; #define PG8_MMA(ai, bj, At, Bt) do { __builtin_amdgcn_s_setprio(1); _Pragma("unroll") for (int m = 0; m < 4; ++m) _Pragma("unroll") for (int n = 0; n < 2; ++n) _Pragma("unroll") for (int k = 0; k < 2; ++k) \
;         acc[ai][bj][m][n] = __builtin_amdgcn_mfma_f32_16x16x32_bf16(Bt[n][k], At[m][k], acc[ai][bj][m][n], 0, 0, 0); __builtin_amdgcn_s_setprio(0); } while (0)
; #define PG8_WAIT_V(n) asm volatile("s_waitcnt vmcnt(" #n ")" ::: "memory")
; #define PG8_WAIT_L(n) asm volatile("s_waitcnt lgkmcnt(" #n ")" ::: "memory")
; #define PG8_BAR __builtin_amdgcn_s_barrier()
; #define PG8_SCHED __builtin_amdgcn_sched_barrier(0)
; template <class Epi, class Sched>
; __device__ __forceinline__ void gemm_phase(LAS unsigned char* lds, const Sched& S, const Epi& E) {
;     ...
;             PG8_STAGE(PG8_SB(0, 1), b2 + xhB, xB0, xB1);
;             PG8_WAIT_V(6); PG8_BAR; PG8_MMA(1, 1, At, B1); PG8_BAR;
;             PG8_LDB(B0, 1, 0); PG8_SCHED; PG8_LDA(At, 1, 0); PG8_STAGE(PG8_SA(0, 1), a2 + xhA, xA0, xA1);
;             PG8_WAIT_L(8); PG8_BAR; PG8_WAIT_L(0); PG8_MMA(0, 0, At, B0); PG8_BAR; PG8_SCHED;
;             PG8_LDB(B1, 1, 1); PG8_STAGE(PG8_SB(1, 0), b3, xB0, xB1);
	s_add_u32 s88, s92, s88
	s_addc_u32 s89, s93, s89
	s_add_i32 s65, vcc_lo, s9
	s_mov_b32 m0, s65
	v_lshl_add_u64 v[160:161], s[88:89], 0, v[136:137]
	global_load_lds_dwordx4 v136, s[88:89]
	s_add_i32 m0, s65, 0x2000
	v_lshl_add_u64 v[138:139], s[88:89], 0, v[156:157]
	global_load_lds_dwordx4 v156, s[88:89]
	s_waitcnt vmcnt(6)
	s_barrier
	s_setprio 1
	v_mfma_f32_16x16x32_bf16 v[28:31], v[230:233], v[198:201], v[28:31]
	v_mfma_f32_16x16x32_bf16 v[24:27], v[238:241], v[198:201], v[24:27]
	v_mfma_f32_16x16x32_bf16 v[20:23], v[230:233], v[206:209], v[20:23]
	v_mfma_f32_16x16x32_bf16 v[16:19], v[238:241], v[206:209], v[16:19]
	v_mfma_f32_16x16x32_bf16 v[12:15], v[230:233], v[214:217], v[12:15]
	v_mfma_f32_16x16x32_bf16 v[8:11], v[238:241], v[214:217], v[8:11]
	v_mfma_f32_16x16x32_bf16 v[4:7], v[230:233], v[222:225], v[4:7]
	v_mfma_f32_16x16x32_bf16 v[0:3], v[238:241], v[222:225], v[0:3]
	v_mfma_f32_16x16x32_bf16 v[28:31], v[234:237], v[202:205], v[28:31]
	v_mfma_f32_16x16x32_bf16 v[24:27], v[242:245], v[202:205], v[24:27]
	v_mfma_f32_16x16x32_bf16 v[20:23], v[234:237], v[210:213], v[20:23]
	v_mfma_f32_16x16x32_bf16 v[16:19], v[242:245], v[210:213], v[16:19]
	v_mfma_f32_16x16x32_bf16 v[12:15], v[234:237], v[218:221], v[12:15]
	v_mfma_f32_16x16x32_bf16 v[8:11], v[242:245], v[218:221], v[8:11]
	v_mfma_f32_16x16x32_bf16 v[4:7], v[234:237], v[226:229], v[4:7]
	v_mfma_f32_16x16x32_bf16 v[0:3], v[242:245], v[226:229], v[0:3]
	s_setprio 0
	s_add_i32 s65, 0, 0x18000
	v_add_u32_e32 v136, s65, v184
	s_barrier
	ds_read_b128 v[156:159], v136
	ds_read_b128 v[186:189], v136 offset:1024
	ds_read_b128 v[190:193], v136 offset:2048
	ds_read_b128 v[194:197], v136 offset:3072
	s_add_u32 s54, s54, s82
	s_addc_u32 s55, s55, s83
	s_mov_b32 m0, s51
	v_lshl_add_u64 v[154:155], s[54:55], 0, v[154:155]
	ds_read_b128 v[198:201], v185 offset:32768
	ds_read_b128 v[202:205], v185 offset:33792
	ds_read_b128 v[206:209], v185 offset:34816
	ds_read_b128 v[210:213], v185 offset:35840
	ds_read_b128 v[214:217], v185 offset:36864
	ds_read_b128 v[218:221], v185 offset:37888
	ds_read_b128 v[222:225], v185 offset:38912
	ds_read_b128 v[226:229], v185 offset:39936
	global_load_lds_dwordx4 v[154:155], off
	v_lshl_add_u64 v[152:153], s[54:55], 0, v[152:153]
	s_mov_b32 m0, s8
	s_nop 0
	global_load_lds_dwordx4 v[152:153], off
	s_waitcnt lgkmcnt(8)
	s_barrier
	s_waitcnt lgkmcnt(0)
	s_setprio 1
	v_mfma_f32_16x16x32_bf16 v[124:127], v[156:159], v[198:201], v[124:127]
	v_mfma_f32_16x16x32_bf16 v[120:123], v[190:193], v[198:201], v[120:123]
	v_mfma_f32_16x16x32_bf16 v[116:119], v[156:159], v[206:209], v[116:119]
	v_mfma_f32_16x16x32_bf16 v[112:115], v[190:193], v[206:209], v[112:115]
	v_mfma_f32_16x16x32_bf16 v[108:111], v[156:159], v[214:217], v[108:111]
	v_mfma_f32_16x16x32_bf16 v[104:107], v[190:193], v[214:217], v[104:107]
	v_mfma_f32_16x16x32_bf16 v[100:103], v[156:159], v[222:225], v[100:103]
	v_mfma_f32_16x16x32_bf16 v[96:99], v[190:193], v[222:225], v[96:99]
	v_mfma_f32_16x16x32_bf16 v[124:127], v[186:189], v[202:205], v[124:127]
	v_mfma_f32_16x16x32_bf16 v[120:123], v[194:197], v[202:205], v[120:123]
	v_mfma_f32_16x16x32_bf16 v[116:119], v[186:189], v[210:213], v[116:119]
	v_mfma_f32_16x16x32_bf16 v[112:115], v[194:197], v[210:213], v[112:115]
	v_mfma_f32_16x16x32_bf16 v[108:111], v[186:189], v[218:221], v[108:111]
	v_mfma_f32_16x16x32_bf16 v[104:107], v[194:197], v[218:221], v[104:107]
	v_mfma_f32_16x16x32_bf16 v[100:103], v[186:189], v[226:229], v[100:103]
	v_mfma_f32_16x16x32_bf16 v[96:99], v[194:197], v[226:229], v[96:99]
	s_setprio 0
	s_barrier
	s_add_i32 s54, 0, 0x1c000
	s_add_i32 s55, s65, s9
	v_add_u32_e32 v136, s54, v184
	v_lshl_add_u64 v[242:243], v[246:247], 0, s[44:45]
	s_mov_b32 m0, s55
	ds_read_b128 v[152:155], v136
	ds_read_b128 v[230:233], v136 offset:1024
	ds_read_b128 v[234:237], v136 offset:2048
	ds_read_b128 v[238:241], v136 offset:3072
	global_load_lds_dwordx4 v[242:243], off
	v_lshl_add_u64 v[242:243], v[248:249], 0, s[44:45]
	s_add_i32 m0, s55, 0x2000
	s_nop 0
	global_load_lds_dwordx4 v[242:243], off
	s_barrier
; #define PG8_STAGE(bufoff, gbase, v0, v1) do { \
;         __builtin_amdgcn_global_load_lds((const unsigned*)((const char*)(gbase) + (v0)), (LAS unsigned*)(lds + (bufoff) + ldsw), 16, 0, 0); \
;         __builtin_amdgcn_global_load_lds((const unsigned*)((const char*)(gbase) + (v1)), (LAS unsigned*)(lds + (bufoff) + ldsw + 8192), 16, 0, 0); } while (0)
; #define PG8_LDA(dst, b, h) do { _Pragma("unroll") for (int m = 0; m < 4; ++m) _Pragma("unroll") for (int k = 0; k < 2; ++k) dst[m][k] = *(const LAS bf16x8*)(lds + PG8_SA(b, h) + aoff + m * 2048 + k * 1024); } while (0)
; #define PG8_MMA(ai, bj, At, Bt) do { __builtin_amdgcn_s_setprio(1); _Pragma("unroll") for (int m = 0; m < 4; ++m) _Pragma("unroll") for (int n = 0; n < 2; ++n) _Pragma("unroll") for (int k = 0; k < 2; ++k) \
;         acc[ai][bj][m][n] = __builtin_amdgcn_mfma_f32_16x16x32_bf16(Bt[n][k], At[m][k], acc[ai][bj][m][n], 0, 0, 0); __builtin_amdgcn_s_setprio(0); } while (0)
; #define PG8_WAIT_V(n) asm volatile("s_waitcnt vmcnt(" #n ")" ::: "memory")
; #define PG8_WAIT_L(n) asm volatile("s_waitcnt lgkmcnt(" #n ")" ::: "memory")
; #define PG8_BAR __builtin_amdgcn_s_barrier()
; #define PG8_SCHED __builtin_amdgcn_sched_barrier(0)
; template <class Epi, class Sched>
; __device__ __forceinline__ void gemm_phase(LAS unsigned char* lds, const Sched& S, const Epi& E) {
;     ...
;             const bool last = (t == nt - 2);
;             const char* a1 = cA + (size_t)(t + 1) * kstep;
;             const char* a2 = last ? nA : cA + (size_t)(t + 2) * kstep; const char* b2 = last ? nB : cB + (size_t)(t + 2) * kstep;
;             const char* a3 = a2 + kstep; const char* b3 = b2 + kstep;
;             const unsigned xA0 = last ? nvA0 : vA0, xA1 = last ? nvA1 : vA1, xB0 = last ? nvB0 : vB0, xB1 = last ? nvB1 : vB1;
;             const size_t xhA = last ? nhA : hA, xhB = last ? nhB : hB;
;     ...
;             PG8_BAR; PG8_WAIT_L(0); PG8_MMA(0, 1, At, B1); PG8_BAR;
;             PG8_LDA(At, 1, 1); PG8_STAGE(PG8_SA(1, 0), a3, xA0, xA1);
;             PG8_BAR; PG8_WAIT_L(0); PG8_MMA(1, 0, At, B0); PG8_BAR; PG8_SCHED;
;             PG8_STAGE(PG8_SB(1, 1), b3 + xhB, xB0, xB1);
;             PG8_WAIT_V(6); PG8_BAR; PG8_MMA(1, 1, At, B1); PG8_BAR;
	s_waitcnt lgkmcnt(0)
	s_setprio 1
	v_mfma_f32_16x16x32_bf16 v[92:95], v[152:155], v[198:201], v[92:95]
	v_mfma_f32_16x16x32_bf16 v[88:91], v[234:237], v[198:201], v[88:91]
	v_mfma_f32_16x16x32_bf16 v[84:87], v[152:155], v[206:209], v[84:87]
	v_mfma_f32_16x16x32_bf16 v[80:83], v[234:237], v[206:209], v[80:83]
	v_mfma_f32_16x16x32_bf16 v[76:79], v[152:155], v[214:217], v[76:79]
	v_mfma_f32_16x16x32_bf16 v[72:75], v[234:237], v[214:217], v[72:75]
	v_mfma_f32_16x16x32_bf16 v[68:71], v[152:155], v[222:225], v[68:71]
	v_mfma_f32_16x16x32_bf16 v[64:67], v[234:237], v[222:225], v[64:67]
	v_mfma_f32_16x16x32_bf16 v[92:95], v[230:233], v[202:205], v[92:95]
	v_mfma_f32_16x16x32_bf16 v[88:91], v[238:241], v[202:205], v[88:91]
	v_mfma_f32_16x16x32_bf16 v[84:87], v[230:233], v[210:213], v[84:87]
	v_mfma_f32_16x16x32_bf16 v[80:83], v[238:241], v[210:213], v[80:83]
	v_mfma_f32_16x16x32_bf16 v[76:79], v[230:233], v[218:221], v[76:79]
	v_mfma_f32_16x16x32_bf16 v[72:75], v[238:241], v[218:221], v[72:75]
	v_mfma_f32_16x16x32_bf16 v[68:71], v[230:233], v[226:229], v[68:71]
	v_mfma_f32_16x16x32_bf16 v[64:67], v[238:241], v[226:229], v[64:67]
	s_setprio 0
	s_mov_b32 m0, s21
	v_lshl_add_u64 v[242:243], v[250:251], 0, s[44:45]
	s_barrier
	ds_read_b128 v[198:201], v185 offset:49152
	ds_read_b128 v[202:205], v185 offset:50176
	ds_read_b128 v[206:209], v185 offset:51200
	ds_read_b128 v[210:213], v185 offset:52224
	ds_read_b128 v[214:217], v185 offset:53248
	ds_read_b128 v[218:221], v185 offset:54272
	ds_read_b128 v[222:225], v185 offset:55296
	ds_read_b128 v[226:229], v185 offset:56320
	global_load_lds_dwordx4 v[242:243], off
	v_lshl_add_u64 v[140:141], v[140:141], 0, s[44:45]
	s_mov_b32 m0, s24
	s_nop 0
	global_load_lds_dwordx4 v[140:141], off
	s_barrier
	s_waitcnt lgkmcnt(0)
	s_setprio 1
	v_mfma_f32_16x16x32_bf16 v[60:63], v[156:159], v[198:201], v[60:63]
	v_mfma_f32_16x16x32_bf16 v[56:59], v[190:193], v[198:201], v[56:59]
	v_mfma_f32_16x16x32_bf16 v[52:55], v[156:159], v[206:209], v[52:55]
	v_mfma_f32_16x16x32_bf16 v[48:51], v[190:193], v[206:209], v[48:51]
	v_mfma_f32_16x16x32_bf16 v[44:47], v[156:159], v[214:217], v[44:47]
	v_mfma_f32_16x16x32_bf16 v[40:43], v[190:193], v[214:217], v[40:43]
	v_mfma_f32_16x16x32_bf16 v[36:39], v[156:159], v[222:225], v[36:39]
	v_mfma_f32_16x16x32_bf16 v[32:35], v[190:193], v[222:225], v[32:35]
	v_mfma_f32_16x16x32_bf16 v[60:63], v[186:189], v[202:205], v[60:63]
	v_mfma_f32_16x16x32_bf16 v[56:59], v[194:197], v[202:205], v[56:59]
	v_mfma_f32_16x16x32_bf16 v[52:55], v[186:189], v[210:213], v[52:55]
	v_mfma_f32_16x16x32_bf16 v[48:51], v[194:197], v[210:213], v[48:51]
	v_mfma_f32_16x16x32_bf16 v[44:47], v[186:189], v[218:221], v[44:47]
	v_mfma_f32_16x16x32_bf16 v[40:43], v[194:197], v[218:221], v[40:43]
	v_mfma_f32_16x16x32_bf16 v[36:39], v[186:189], v[226:229], v[36:39]
	v_mfma_f32_16x16x32_bf16 v[32:35], v[194:197], v[226:229], v[32:35]
	s_setprio 0
	s_barrier
	s_add_i32 s54, s54, s9
	v_lshl_add_u64 v[140:141], v[160:161], 0, s[44:45]
	s_mov_b32 m0, s54
	v_lshl_add_u64 v[138:139], v[138:139], 0, s[44:45]
	global_load_lds_dwordx4 v[140:141], off
	s_add_i32 m0, s54, 0x2000
	s_nop 0
	global_load_lds_dwordx4 v[138:139], off
	s_waitcnt vmcnt(6)
	s_barrier
	s_setprio 1
	v_mfma_f32_16x16x32_bf16 v[28:31], v[152:155], v[198:201], v[28:31]
	v_mfma_f32_16x16x32_bf16 v[24:27], v[234:237], v[198:201], v[24:27]
	v_mfma_f32_16x16x32_bf16 v[20:23], v[152:155], v[206:209], v[20:23]
	v_mfma_f32_16x16x32_bf16 v[16:19], v[234:237], v[206:209], v[16:19]
	v_mfma_f32_16x16x32_bf16 v[12:15], v[152:155], v[214:217], v[12:15]
	v_mfma_f32_16x16x32_bf16 v[8:11], v[234:237], v[214:217], v[8:11]
	v_mfma_f32_16x16x32_bf16 v[4:7], v[152:155], v[222:225], v[4:7]
	v_mfma_f32_16x16x32_bf16 v[0:3], v[234:237], v[222:225], v[0:3]
	v_mfma_f32_16x16x32_bf16 v[28:31], v[230:233], v[202:205], v[28:31]
	v_mfma_f32_16x16x32_bf16 v[24:27], v[238:241], v[202:205], v[24:27]
	v_mfma_f32_16x16x32_bf16 v[20:23], v[230:233], v[210:213], v[20:23]
	v_mfma_f32_16x16x32_bf16 v[16:19], v[238:241], v[210:213], v[16:19]
	v_mfma_f32_16x16x32_bf16 v[12:15], v[230:233], v[218:221], v[12:15]
	v_mfma_f32_16x16x32_bf16 v[8:11], v[238:241], v[218:221], v[8:11]
	v_mfma_f32_16x16x32_bf16 v[4:7], v[230:233], v[226:229], v[4:7]
	v_mfma_f32_16x16x32_bf16 v[0:3], v[238:241], v[226:229], v[0:3]
	s_setprio 0
	s_add_u32 s34, s34, 0x100
	s_addc_u32 s35, s35, 0
	s_add_u32 s70, s70, 0x100
	s_addc_u32 s71, s71, 0
	s_cmp_ge_i32 s49, s36
	s_cbranch_scc1 .Lrot_exit_1
	s_cmp_eq_u32 s39, s49
	s_cselect_b64 s[54:55], -1, 0
	s_and_b64 vcc, exec, s[54:55]
	v_mov_b64_e32 v[152:153], v[144:145]
	v_mov_b64_e32 v[154:155], v[142:143]
	s_mov_b64 s[88:89], s[68:69]
	s_mov_b64 s[82:83], s[66:67]
	v_mov_b32_e32 v156, v148
	v_mov_b32_e32 v136, v146
	s_mov_b64 s[92:93], s[42:43]
	s_cbranch_vccnz .Lrot_join_1
	v_mov_b64_e32 v[152:153], v[128:129]
	v_mov_b64_e32 v[154:155], v[132:133]
	s_mov_b64 s[88:89], s[12:13]
	s_mov_b64 s[82:83], s[14:15]
	v_mov_b32_e32 v156, v130
	v_mov_b32_e32 v136, v131
	s_mov_b64 s[92:93], s[70:71]

; #define PG8_STAGE(bufoff, gbase, v0, v1) do { \
;         __builtin_amdgcn_global_load_lds((const unsigned*)((const char*)(gbase) + (v0)), (LAS unsigned*)(lds + (bufoff) + ldsw), 16, 0, 0); \
;         __builtin_amdgcn_global_load_lds((const unsigned*)((const char*)(gbase) + (v1)), (LAS unsigned*)(lds + (bufoff) + ldsw + 8192), 16, 0, 0); } while (0)
; #define PG8_LDA(dst, b, h) do { _Pragma("unroll") for (int m = 0; m < 4; ++m) _Pragma("unroll") for (int k = 0; k < 2; ++k) dst[m][k] = *(const LAS bf16x8*)(lds + PG8_SA(b, h) + aoff + m * 2048 + k * 1024); } while (0)
; #define PG8_LDB(dst, b, h) do { _Pragma("unroll") for (int n = 0; n < 2; ++n) _Pragma("unroll") for (int k = 0; k < 2; ++k) dst[n][k] = *(const LAS bf16x8*)(lds + PG8_SB(b, h) + boff + n * 2048 + k * 1024); } while (0)
; #define PG8_MMA(ai, bj, At, Bt) do { __builtin_amdgcn_s_setprio(1); _Pragma("unroll") for (int m = 0; m < 4; ++m) _Pragma("unroll") for (int n = 0; n < 2; ++n) _Pragma("unroll") for (int k = 0; k < 2; ++k) \
;         acc[ai][bj][m][n] = __builtin_amdgcn_mfma_f32_16x16x32_bf16(Bt[n][k], At[m][k], acc[ai][bj][m][n], 0, 0, 0); __builtin_amdgcn_s_setprio(0); } while (0)
; #define PG8_WAIT_L(n) asm volatile("s_waitcnt lgkmcnt(" #n ")" ::: "memory")
; template <class Epi, class Sched>
; __device__ __forceinline__ void gemm_phase(LAS unsigned char* lds, const Sched& S, const Epi& E) {
;     ...
;             const bool last = (t == nt - 2);
;             const char* a1 = cA + (size_t)(t + 1) * kstep;
;             const char* a2 = last ? nA : cA + (size_t)(t + 2) * kstep; const char* b2 = last ? nB : cB + (size_t)(t + 2) * kstep;
;             const char* a3 = a2 + kstep; const char* b3 = b2 + kstep;
;             const unsigned xA0 = last ? nvA0 : vA0, xA1 = last ? nvA1 : vA1, xB0 = last ? nvB0 : vB0, xB1 = last ? nvB1 : vB1;
;             const size_t xhA = last ? nhA : hA, xhB = last ? nhB : hB;
;             PG8_LDB(B0, 0, 0); PG8_SCHED; PG8_LDA(At, 0, 0); PG8_STAGE(PG8_SA(1, 1), a1 + hA, vA0, vA1);
;             PG8_WAIT_L(8); PG8_BAR; PG8_WAIT_L(0); PG8_MMA(0, 0, At, B0); PG8_BAR; PG8_SCHED;
;             PG8_LDB(B1, 0, 1); PG8_STAGE(PG8_SB(0, 0), b2, xB0, xB1);
;             PG8_BAR; PG8_WAIT_L(0); PG8_MMA(0, 1, At, B1); PG8_BAR;
;             PG8_LDA(At, 0, 1); PG8_STAGE(PG8_SA(0, 0), a2, xA0, xA1);
;             PG8_BAR; PG8_WAIT_L(0); PG8_MMA(1, 0, At, B0); PG8_BAR; PG8_SCHED;
.LBB0_745:
	s_add_u32 s23, s34, 0xfff80080
	s_addc_u32 s71, s35, -1
	s_and_b64 s[42:43], exec, s[42:43]
	s_cselect_b32 s43, s25, s71
	s_cselect_b32 s42, s24, s23
	s_add_i32 s23, 0, 0x10000
	v_add_u32_e32 v138, s23, v147
	ds_read_b128 v[150:153], v138
	ds_read_b128 v[154:157], v138 offset:1024
	ds_read_b128 v[158:161], v138 offset:2048
	ds_read_b128 v[182:185], v138 offset:3072
	v_lshl_add_u64 v[138:139], s[34:35], 0, v[136:137]
	s_add_i32 m0, s50, 0xc000
	ds_read_b128 v[186:189], v148
	ds_read_b128 v[190:193], v148 offset:1024
	ds_read_b128 v[194:197], v148 offset:2048
	ds_read_b128 v[198:201], v148 offset:3072
	ds_read_b128 v[202:205], v148 offset:4096
	ds_read_b128 v[206:209], v148 offset:5120
	ds_read_b128 v[210:213], v148 offset:6144
	ds_read_b128 v[214:217], v148 offset:7168
	global_load_lds_dwordx4 v[138:139], off
	v_lshl_add_u64 v[138:139], s[34:35], 0, v[132:133]
	s_add_i32 m0, s50, 0xe000
	s_nop 0
	global_load_lds_dwordx4 v[138:139], off
	s_waitcnt lgkmcnt(8)
	s_barrier
	s_waitcnt lgkmcnt(0)
	s_setprio 1
	v_mfma_f32_16x16x32_bf16 v[124:127], v[150:153], v[186:189], v[124:127]
	v_mfma_f32_16x16x32_bf16 v[120:123], v[158:161], v[186:189], v[120:123]
	v_mfma_f32_16x16x32_bf16 v[108:111], v[150:153], v[194:197], v[108:111]
	v_mfma_f32_16x16x32_bf16 v[104:107], v[158:161], v[194:197], v[104:107]
	v_mfma_f32_16x16x32_bf16 v[92:95], v[150:153], v[202:205], v[92:95]
	v_mfma_f32_16x16x32_bf16 v[88:91], v[158:161], v[202:205], v[88:91]
	v_mfma_f32_16x16x32_bf16 v[76:79], v[150:153], v[210:213], v[76:79]
	v_mfma_f32_16x16x32_bf16 v[72:75], v[158:161], v[210:213], v[72:75]
	v_mfma_f32_16x16x32_bf16 v[124:127], v[154:157], v[190:193], v[124:127]
	v_mfma_f32_16x16x32_bf16 v[120:123], v[182:185], v[190:193], v[120:123]
	v_mfma_f32_16x16x32_bf16 v[108:111], v[154:157], v[198:201], v[108:111]
	v_mfma_f32_16x16x32_bf16 v[104:107], v[182:185], v[198:201], v[104:107]
	v_mfma_f32_16x16x32_bf16 v[92:95], v[154:157], v[206:209], v[92:95]
	v_mfma_f32_16x16x32_bf16 v[88:91], v[182:185], v[206:209], v[88:91]
	v_mfma_f32_16x16x32_bf16 v[76:79], v[154:157], v[214:217], v[76:79]
	v_mfma_f32_16x16x32_bf16 v[72:75], v[182:185], v[214:217], v[72:75]
	s_setprio 0
	s_barrier
	s_add_i32 s71, 0, 0x14000
	v_add_u32_e32 v138, s71, v147
	s_add_i32 s23, s23, s49
	ds_read_b128 v[218:221], v138
	ds_read_b128 v[222:225], v138 offset:1024
	ds_read_b128 v[226:229], v138 offset:2048
	ds_read_b128 v[230:233], v138 offset:3072
	v_lshl_add_u64 v[138:139], s[40:41], 0, v[142:143]
	s_mov_b32 m0, s23
	v_lshl_add_u64 v[140:141], s[40:41], 0, v[134:135]
	global_load_lds_dwordx4 v[138:139], off
	s_add_i32 m0, s23, 0x2000
	s_nop 0
	global_load_lds_dwordx4 v[140:141], off
	s_barrier
	s_waitcnt lgkmcnt(0)
	s_setprio 1
	v_mfma_f32_16x16x32_bf16 v[116:119], v[218:221], v[186:189], v[116:119]
	v_mfma_f32_16x16x32_bf16 v[112:115], v[226:229], v[186:189], v[112:115]
	v_mfma_f32_16x16x32_bf16 v[100:103], v[218:221], v[194:197], v[100:103]
	v_mfma_f32_16x16x32_bf16 v[96:99], v[226:229], v[194:197], v[96:99]
	v_mfma_f32_16x16x32_bf16 v[84:87], v[218:221], v[202:205], v[84:87]
	v_mfma_f32_16x16x32_bf16 v[80:83], v[226:229], v[202:205], v[80:83]
	v_mfma_f32_16x16x32_bf16 v[68:71], v[218:221], v[210:213], v[68:71]
	v_mfma_f32_16x16x32_bf16 v[64:67], v[226:229], v[210:213], v[64:67]
	v_mfma_f32_16x16x32_bf16 v[116:119], v[222:225], v[190:193], v[116:119]
	v_mfma_f32_16x16x32_bf16 v[112:115], v[230:233], v[190:193], v[112:115]
	v_mfma_f32_16x16x32_bf16 v[100:103], v[222:225], v[198:201], v[100:103]
	v_mfma_f32_16x16x32_bf16 v[96:99], v[230:233], v[198:201], v[96:99]
	v_mfma_f32_16x16x32_bf16 v[84:87], v[222:225], v[206:209], v[84:87]
	v_mfma_f32_16x16x32_bf16 v[80:83], v[230:233], v[206:209], v[80:83]
	v_mfma_f32_16x16x32_bf16 v[68:71], v[222:225], v[214:217], v[68:71]
	v_mfma_f32_16x16x32_bf16 v[64:67], v[230:233], v[214:217], v[64:67]
	s_setprio 0
	s_mov_b32 m0, s50
	v_lshl_add_u64 v[234:235], s[42:43], 0, v[142:143]
	s_barrier
	ds_read_b128 v[186:189], v148 offset:16384
	ds_read_b128 v[190:193], v148 offset:17408
	ds_read_b128 v[194:197], v148 offset:18432
	ds_read_b128 v[198:201], v148 offset:19456
	ds_read_b128 v[202:205], v148 offset:20480
	ds_read_b128 v[206:209], v148 offset:21504
	ds_read_b128 v[210:213], v148 offset:22528
	ds_read_b128 v[214:217], v148 offset:23552
	global_load_lds_dwordx4 v[234:235], off
	v_lshl_add_u64 v[236:237], s[42:43], 0, v[134:135]
	s_mov_b32 m0, s51
	s_nop 0
	global_load_lds_dwordx4 v[236:237], off
	s_barrier
	s_waitcnt lgkmcnt(0)
	s_setprio 1
	v_mfma_f32_16x16x32_bf16 v[60:63], v[150:153], v[186:189], v[60:63]
	v_mfma_f32_16x16x32_bf16 v[56:59], v[158:161], v[186:189], v[56:59]
	v_mfma_f32_16x16x32_bf16 v[44:47], v[150:153], v[194:197], v[44:47]
	v_mfma_f32_16x16x32_bf16 v[40:43], v[158:161], v[194:197], v[40:43]
	v_mfma_f32_16x16x32_bf16 v[28:31], v[150:153], v[202:205], v[28:31]
	v_mfma_f32_16x16x32_bf16 v[24:27], v[158:161], v[202:205], v[24:27]
	v_mfma_f32_16x16x32_bf16 v[12:15], v[150:153], v[210:213], v[12:15]
	v_mfma_f32_16x16x32_bf16 v[8:11], v[158:161], v[210:213], v[8:11]
	v_mfma_f32_16x16x32_bf16 v[60:63], v[154:157], v[190:193], v[60:63]
	v_mfma_f32_16x16x32_bf16 v[56:59], v[182:185], v[190:193], v[56:59]
	v_mfma_f32_16x16x32_bf16 v[44:47], v[154:157], v[198:201], v[44:47]
	v_mfma_f32_16x16x32_bf16 v[40:43], v[182:185], v[198:201], v[40:43]
	v_mfma_f32_16x16x32_bf16 v[28:31], v[154:157], v[206:209], v[28:31]
	v_mfma_f32_16x16x32_bf16 v[24:27], v[182:185], v[206:209], v[24:27]
	v_mfma_f32_16x16x32_bf16 v[12:15], v[154:157], v[214:217], v[12:15]
	v_mfma_f32_16x16x32_bf16 v[8:11], v[182:185], v[214:217], v[8:11]
	s_setprio 0
	s_barrier
; #define PG8_STAGE(bufoff, gbase, v0, v1) do { \
;         __builtin_amdgcn_global_load_lds((const unsigned*)((const char*)(gbase) + (v0)), (LAS unsigned*)(lds + (bufoff) + ldsw), 16, 0, 0); \
;         __builtin_amdgcn_global_load_lds((const unsigned*)((const char*)(gbase) + (v1)), (LAS unsigned*)(lds + (bufoff) + ldsw + 8192), 16, 0, 0); } while (0)
; #define PG8_LDA(dst, b, h) do { _Pragma("unroll") for (int m = 0; m < 4; ++m) _Pragma("unroll") for (int k = 0; k < 2; ++k) dst[m][k] = *(const LAS bf16x8*)(lds + PG8_SA(b, h) + aoff + m * 2048 + k * 1024); } while (0)
; #define PG8_LDB(dst, b, h) do { _Pragma("unroll") for (int n = 0; n < 2; ++n) _Pragma("unroll") for (int k = 0; k < 2; ++k) dst[n][k] = *(const LAS bf16x8*)(lds + PG8_SB(b, h) + boff + n * 2048 + k * 1024); } while (0)
; #define PG8_MMA(ai, bj, At, Bt) do { __builtin_amdgcn_s_setprio(1); _Pragma("unroll") for (int m = 0; m < 4; ++m) _Pragma("unroll") for (int n = 0; n < 2; ++n) _Pragma("unroll") for (int k = 0; k < 2; ++k) \
;         acc[ai][bj][m][n] = __builtin_amdgcn_mfma_f32_16x16x32_bf16(Bt[n][k], At[m][k], acc[ai][bj][m][n], 0, 0, 0); __builtin_amdgcn_s_setprio(0); } while (0)
; #define PG8_WAIT_V(n) asm volatile("s_waitcnt vmcnt(" #n ")" ::: "memory")
; #define PG8_WAIT_L(n) asm volatile("s_waitcnt lgkmcnt(" #n ")" ::: "memory")
; #define PG8_BAR __builtin_amdgcn_s_barrier()
; #define PG8_SCHED __builtin_amdgcn_sched_barrier(0)
; template <class Epi, class Sched>
; __device__ __forceinline__ void gemm_phase(LAS unsigned char* lds, const Sched& S, const Epi& E) {
;     ...
;             PG8_STAGE(PG8_SB(0, 1), b2 + xhB, xB0, xB1);
;             PG8_WAIT_V(6); PG8_BAR; PG8_MMA(1, 1, At, B1); PG8_BAR;
;             PG8_LDB(B0, 1, 0); PG8_SCHED; PG8_LDA(At, 1, 0); PG8_STAGE(PG8_SA(0, 1), a2 + xhA, xA0, xA1);
;             PG8_WAIT_L(8); PG8_BAR; PG8_WAIT_L(0); PG8_MMA(0, 0, At, B0); PG8_BAR; PG8_SCHED;
;             PG8_LDB(B1, 1, 1); PG8_STAGE(PG8_SB(1, 0), b3, xB0, xB1);
	s_add_u32 s82, s40, 0x80000
	s_addc_u32 s83, s41, 0
	s_add_i32 s23, s71, s49
	v_lshl_add_u64 v[150:151], s[82:83], 0, v[142:143]
	s_mov_b32 m0, s23
	s_nop 0
	global_load_lds_dwordx4 v[150:151], off
	v_lshl_add_u64 v[150:151], s[82:83], 0, v[134:135]
	s_add_i32 m0, s23, 0x2000
	s_nop 0
	global_load_lds_dwordx4 v[150:151], off
	s_waitcnt vmcnt(6)
	s_barrier
	s_setprio 1
	v_mfma_f32_16x16x32_bf16 v[52:55], v[218:221], v[186:189], v[52:55]
	v_mfma_f32_16x16x32_bf16 v[48:51], v[226:229], v[186:189], v[48:51]
	v_mfma_f32_16x16x32_bf16 v[36:39], v[218:221], v[194:197], v[36:39]
	v_mfma_f32_16x16x32_bf16 v[32:35], v[226:229], v[194:197], v[32:35]
	v_mfma_f32_16x16x32_bf16 v[20:23], v[218:221], v[202:205], v[20:23]
	v_mfma_f32_16x16x32_bf16 v[16:19], v[226:229], v[202:205], v[16:19]
	v_mfma_f32_16x16x32_bf16 v[4:7], v[218:221], v[210:213], v[4:7]
	v_mfma_f32_16x16x32_bf16 v[0:3], v[226:229], v[210:213], v[0:3]
	v_mfma_f32_16x16x32_bf16 v[52:55], v[222:225], v[190:193], v[52:55]
	v_mfma_f32_16x16x32_bf16 v[48:51], v[230:233], v[190:193], v[48:51]
	v_mfma_f32_16x16x32_bf16 v[36:39], v[222:225], v[198:201], v[36:39]
	v_mfma_f32_16x16x32_bf16 v[32:35], v[230:233], v[198:201], v[32:35]
	v_mfma_f32_16x16x32_bf16 v[20:23], v[222:225], v[206:209], v[20:23]
	v_mfma_f32_16x16x32_bf16 v[16:19], v[230:233], v[206:209], v[16:19]
	v_mfma_f32_16x16x32_bf16 v[4:7], v[222:225], v[214:217], v[4:7]
	v_mfma_f32_16x16x32_bf16 v[0:3], v[230:233], v[214:217], v[0:3]
	s_setprio 0
	s_add_i32 s23, 0, 0x18000
	v_add_u32_e32 v149, s23, v147
	s_barrier
	ds_read_b128 v[150:153], v149
	ds_read_b128 v[154:157], v149 offset:1024
	ds_read_b128 v[158:161], v149 offset:2048
	ds_read_b128 v[182:185], v149 offset:3072
	s_add_u32 s42, s42, 0x80000
	s_addc_u32 s43, s43, 0
	s_mov_b32 m0, s54
	v_lshl_add_u64 v[218:219], s[42:43], 0, v[142:143]
	ds_read_b128 v[186:189], v148 offset:32768
	ds_read_b128 v[190:193], v148 offset:33792
	ds_read_b128 v[194:197], v148 offset:34816
	ds_read_b128 v[198:201], v148 offset:35840
	ds_read_b128 v[202:205], v148 offset:36864
	ds_read_b128 v[206:209], v148 offset:37888
	ds_read_b128 v[210:213], v148 offset:38912
	ds_read_b128 v[214:217], v148 offset:39936
	global_load_lds_dwordx4 v[218:219], off
	v_lshl_add_u64 v[218:219], s[42:43], 0, v[134:135]
	s_mov_b32 m0, s55
	s_nop 0
	global_load_lds_dwordx4 v[218:219], off
	s_waitcnt lgkmcnt(8)
	s_barrier
	s_waitcnt lgkmcnt(0)
	s_setprio 1
	v_mfma_f32_16x16x32_bf16 v[124:127], v[150:153], v[186:189], v[124:127]
	v_mfma_f32_16x16x32_bf16 v[120:123], v[158:161], v[186:189], v[120:123]
	v_mfma_f32_16x16x32_bf16 v[108:111], v[150:153], v[194:197], v[108:111]
	v_mfma_f32_16x16x32_bf16 v[104:107], v[158:161], v[194:197], v[104:107]
	v_mfma_f32_16x16x32_bf16 v[92:95], v[150:153], v[202:205], v[92:95]
	v_mfma_f32_16x16x32_bf16 v[88:91], v[158:161], v[202:205], v[88:91]
	v_mfma_f32_16x16x32_bf16 v[76:79], v[150:153], v[210:213], v[76:79]
	v_mfma_f32_16x16x32_bf16 v[72:75], v[158:161], v[210:213], v[72:75]
	v_mfma_f32_16x16x32_bf16 v[124:127], v[154:157], v[190:193], v[124:127]
	v_mfma_f32_16x16x32_bf16 v[120:123], v[182:185], v[190:193], v[120:123]
	v_mfma_f32_16x16x32_bf16 v[108:111], v[154:157], v[198:201], v[108:111]
	v_mfma_f32_16x16x32_bf16 v[104:107], v[182:185], v[198:201], v[104:107]
	v_mfma_f32_16x16x32_bf16 v[92:95], v[154:157], v[206:209], v[92:95]
	v_mfma_f32_16x16x32_bf16 v[88:91], v[182:185], v[206:209], v[88:91]
	v_mfma_f32_16x16x32_bf16 v[76:79], v[154:157], v[214:217], v[76:79]
	v_mfma_f32_16x16x32_bf16 v[72:75], v[182:185], v[214:217], v[72:75]
	s_setprio 0
	s_barrier
	s_add_i32 s42, 0, 0x1c000
	s_add_i32 s23, s23, s49
	v_add_u32_e32 v149, s42, v147
	v_lshl_add_u64 v[138:139], v[138:139], 0, s[44:45]
	s_mov_b32 m0, s23
	ds_read_b128 v[218:221], v149
	ds_read_b128 v[222:225], v149 offset:1024
	ds_read_b128 v[226:229], v149 offset:2048
	ds_read_b128 v[230:233], v149 offset:3072
	global_load_lds_dwordx4 v[138:139], off
	v_lshl_add_u64 v[138:139], v[140:141], 0, s[44:45]
	s_add_i32 m0, s23, 0x2000
	s_nop 0
	global_load_lds_dwordx4 v[138:139], off
	s_barrier
; #define PG8_STAGE(bufoff, gbase, v0, v1) do { \
;         __builtin_amdgcn_global_load_lds((const unsigned*)((const char*)(gbase) + (v0)), (LAS unsigned*)(lds + (bufoff) + ldsw), 16, 0, 0); \
;         __builtin_amdgcn_global_load_lds((const unsigned*)((const char*)(gbase) + (v1)), (LAS unsigned*)(lds + (bufoff) + ldsw + 8192), 16, 0, 0); } while (0)
; #define PG8_LDA(dst, b, h) do { _Pragma("unroll") for (int m = 0; m < 4; ++m) _Pragma("unroll") for (int k = 0; k < 2; ++k) dst[m][k] = *(const LAS bf16x8*)(lds + PG8_SA(b, h) + aoff + m * 2048 + k * 1024); } while (0)
; #define PG8_MMA(ai, bj, At, Bt) do { __builtin_amdgcn_s_setprio(1); _Pragma("unroll") for (int m = 0; m < 4; ++m) _Pragma("unroll") for (int n = 0; n < 2; ++n) _Pragma("unroll") for (int k = 0; k < 2; ++k) \
;         acc[ai][bj][m][n] = __builtin_amdgcn_mfma_f32_16x16x32_bf16(Bt[n][k], At[m][k], acc[ai][bj][m][n], 0, 0, 0); __builtin_amdgcn_s_setprio(0); } while (0)
; #define PG8_WAIT_V(n) asm volatile("s_waitcnt vmcnt(" #n ")" ::: "memory")
; #define PG8_WAIT_L(n) asm volatile("s_waitcnt lgkmcnt(" #n ")" ::: "memory")
; #define PG8_BAR __builtin_amdgcn_s_barrier()
; #define PG8_SCHED __builtin_amdgcn_sched_barrier(0)
; template <class Epi, class Sched>
; __device__ __forceinline__ void gemm_phase(LAS unsigned char* lds, const Sched& S, const Epi& E) {
;     ...
;         for (int t = 0; t < nt; t += 2) {
;             const bool last = (t == nt - 2);
;             const char* a1 = cA + (size_t)(t + 1) * kstep;
;             const char* a2 = last ? nA : cA + (size_t)(t + 2) * kstep; const char* b2 = last ? nB : cB + (size_t)(t + 2) * kstep;
;             const char* a3 = a2 + kstep; const char* b3 = b2 + kstep;
;             const unsigned xA0 = last ? nvA0 : vA0, xA1 = last ? nvA1 : vA1, xB0 = last ? nvB0 : vB0, xB1 = last ? nvB1 : vB1;
;             const size_t xhA = last ? nhA : hA, xhB = last ? nhB : hB;
;     ...
;             PG8_BAR; PG8_WAIT_L(0); PG8_MMA(0, 1, At, B1); PG8_BAR;
;             PG8_LDA(At, 1, 1); PG8_STAGE(PG8_SA(1, 0), a3, xA0, xA1);
;             PG8_BAR; PG8_WAIT_L(0); PG8_MMA(1, 0, At, B0); PG8_BAR; PG8_SCHED;
;             PG8_STAGE(PG8_SB(1, 1), b3 + xhB, xB0, xB1);
;             PG8_WAIT_V(6); PG8_BAR; PG8_MMA(1, 1, At, B1); PG8_BAR;
	s_waitcnt lgkmcnt(0)
	s_setprio 1
	v_mfma_f32_16x16x32_bf16 v[116:119], v[218:221], v[186:189], v[116:119]
	v_mfma_f32_16x16x32_bf16 v[112:115], v[226:229], v[186:189], v[112:115]
	v_mfma_f32_16x16x32_bf16 v[100:103], v[218:221], v[194:197], v[100:103]
	v_mfma_f32_16x16x32_bf16 v[96:99], v[226:229], v[194:197], v[96:99]
	v_mfma_f32_16x16x32_bf16 v[84:87], v[218:221], v[202:205], v[84:87]
	v_mfma_f32_16x16x32_bf16 v[80:83], v[226:229], v[202:205], v[80:83]
	v_mfma_f32_16x16x32_bf16 v[68:71], v[218:221], v[210:213], v[68:71]
	v_mfma_f32_16x16x32_bf16 v[64:67], v[226:229], v[210:213], v[64:67]
	v_mfma_f32_16x16x32_bf16 v[116:119], v[222:225], v[190:193], v[116:119]
	v_mfma_f32_16x16x32_bf16 v[112:115], v[230:233], v[190:193], v[112:115]
	v_mfma_f32_16x16x32_bf16 v[100:103], v[222:225], v[198:201], v[100:103]
	v_mfma_f32_16x16x32_bf16 v[96:99], v[230:233], v[198:201], v[96:99]
	v_mfma_f32_16x16x32_bf16 v[84:87], v[222:225], v[206:209], v[84:87]
	v_mfma_f32_16x16x32_bf16 v[80:83], v[230:233], v[206:209], v[80:83]
	v_mfma_f32_16x16x32_bf16 v[68:71], v[222:225], v[214:217], v[68:71]
	v_mfma_f32_16x16x32_bf16 v[64:67], v[230:233], v[214:217], v[64:67]
	s_setprio 0
	s_mov_b32 m0, s66
	v_lshl_add_u64 v[138:139], v[234:235], 0, s[44:45]
	s_barrier
	ds_read_b128 v[186:189], v148 offset:49152
	ds_read_b128 v[190:193], v148 offset:50176
	ds_read_b128 v[194:197], v148 offset:51200
	ds_read_b128 v[198:201], v148 offset:52224
	ds_read_b128 v[202:205], v148 offset:53248
	ds_read_b128 v[206:209], v148 offset:54272
	ds_read_b128 v[210:213], v148 offset:55296
	ds_read_b128 v[214:217], v148 offset:56320
	global_load_lds_dwordx4 v[138:139], off
	v_lshl_add_u64 v[138:139], v[236:237], 0, s[44:45]
	s_mov_b32 m0, s67
	s_nop 0
	global_load_lds_dwordx4 v[138:139], off
	s_barrier
	s_waitcnt lgkmcnt(0)
	s_setprio 1
	v_mfma_f32_16x16x32_bf16 v[60:63], v[150:153], v[186:189], v[60:63]
	v_mfma_f32_16x16x32_bf16 v[56:59], v[158:161], v[186:189], v[56:59]
	v_mfma_f32_16x16x32_bf16 v[44:47], v[150:153], v[194:197], v[44:47]
	v_mfma_f32_16x16x32_bf16 v[40:43], v[158:161], v[194:197], v[40:43]
	v_mfma_f32_16x16x32_bf16 v[28:31], v[150:153], v[202:205], v[28:31]
	v_mfma_f32_16x16x32_bf16 v[24:27], v[158:161], v[202:205], v[24:27]
	v_mfma_f32_16x16x32_bf16 v[12:15], v[150:153], v[210:213], v[12:15]
	v_mfma_f32_16x16x32_bf16 v[8:11], v[158:161], v[210:213], v[8:11]
	v_mfma_f32_16x16x32_bf16 v[60:63], v[154:157], v[190:193], v[60:63]
	v_mfma_f32_16x16x32_bf16 v[56:59], v[182:185], v[190:193], v[56:59]
	v_mfma_f32_16x16x32_bf16 v[44:47], v[154:157], v[198:201], v[44:47]
	v_mfma_f32_16x16x32_bf16 v[40:43], v[182:185], v[198:201], v[40:43]
	v_mfma_f32_16x16x32_bf16 v[28:31], v[154:157], v[206:209], v[28:31]
	v_mfma_f32_16x16x32_bf16 v[24:27], v[182:185], v[206:209], v[24:27]
	v_mfma_f32_16x16x32_bf16 v[12:15], v[154:157], v[214:217], v[12:15]
	v_mfma_f32_16x16x32_bf16 v[8:11], v[182:185], v[214:217], v[8:11]
	s_setprio 0
	s_barrier
	s_add_u32 s40, s40, 0x80080
	s_addc_u32 s41, s41, 0
	s_add_i32 s23, s42, s49
	v_lshl_add_u64 v[138:139], s[40:41], 0, v[142:143]
	s_mov_b32 m0, s23
	v_lshl_add_u64 v[134:135], s[40:41], 0, v[134:135]
	global_load_lds_dwordx4 v[138:139], off
	s_add_i32 m0, s23, 0x2000
	s_nop 0
	global_load_lds_dwordx4 v[134:135], off
	s_waitcnt vmcnt(6)
	s_barrier
	s_setprio 1
	v_mfma_f32_16x16x32_bf16 v[52:55], v[218:221], v[186:189], v[52:55]
	v_mfma_f32_16x16x32_bf16 v[48:51], v[226:229], v[186:189], v[48:51]
	v_mfma_f32_16x16x32_bf16 v[36:39], v[218:221], v[194:197], v[36:39]
	v_mfma_f32_16x16x32_bf16 v[32:35], v[226:229], v[194:197], v[32:35]
	v_mfma_f32_16x16x32_bf16 v[20:23], v[218:221], v[202:205], v[20:23]
	v_mfma_f32_16x16x32_bf16 v[16:19], v[226:229], v[202:205], v[16:19]
	v_mfma_f32_16x16x32_bf16 v[4:7], v[218:221], v[210:213], v[4:7]
	v_mfma_f32_16x16x32_bf16 v[0:3], v[226:229], v[210:213], v[0:3]
	v_mfma_f32_16x16x32_bf16 v[52:55], v[222:225], v[190:193], v[52:55]
	v_mfma_f32_16x16x32_bf16 v[48:51], v[230:233], v[190:193], v[48:51]
	v_mfma_f32_16x16x32_bf16 v[36:39], v[222:225], v[198:201], v[36:39]
	v_mfma_f32_16x16x32_bf16 v[32:35], v[230:233], v[198:201], v[32:35]
	v_mfma_f32_16x16x32_bf16 v[20:23], v[222:225], v[206:209], v[20:23]
	v_mfma_f32_16x16x32_bf16 v[16:19], v[230:233], v[206:209], v[16:19]
	v_mfma_f32_16x16x32_bf16 v[4:7], v[222:225], v[214:217], v[4:7]
	v_mfma_f32_16x16x32_bf16 v[0:3], v[230:233], v[214:217], v[0:3]
	s_setprio 0
	s_add_i32 s21, s21, 2
	s_add_u32 s34, s34, 0x100
	s_addc_u32 s35, s35, 0
	s_add_u32 s38, s38, 0x100
	s_addc_u32 s39, s39, 0
	s_cmp_gt_u32 s21, 29
	s_cbranch_scc1 .Lrot_exit_2
	s_cmp_eq_u32 s21, 28
	s_cselect_b64 s[42:43], -1, 0
	s_and_b64 vcc, exec, s[42:43]
	v_mov_b64_e32 v[134:135], v[130:131]
	v_mov_b64_e32 v[142:143], v[128:129]
	s_mov_b64 s[40:41], s[26:27]
	s_cbranch_vccnz .Lrot_join_2
	v_mov_b64_e32 v[134:135], v[132:133]
	v_mov_b64_e32 v[142:143], v[136:137]
	s_mov_b64 s[40:41], s[38:39]

; #define PG8_STAGE(bufoff, gbase, v0, v1) do { \
;         __builtin_amdgcn_global_load_lds((const unsigned*)((const char*)(gbase) + (v0)), (LAS unsigned*)(lds + (bufoff) + ldsw), 16, 0, 0); \
;         __builtin_amdgcn_global_load_lds((const unsigned*)((const char*)(gbase) + (v1)), (LAS unsigned*)(lds + (bufoff) + ldsw + 8192), 16, 0, 0); } while (0)
; #define PG8_LDA(dst, b, h) do { _Pragma("unroll") for (int m = 0; m < 4; ++m) _Pragma("unroll") for (int k = 0; k < 2; ++k) dst[m][k] = *(const LAS bf16x8*)(lds + PG8_SA(b, h) + aoff + m * 2048 + k * 1024); } while (0)
; #define PG8_LDB(dst, b, h) do { _Pragma("unroll") for (int n = 0; n < 2; ++n) _Pragma("unroll") for (int k = 0; k < 2; ++k) dst[n][k] = *(const LAS bf16x8*)(lds + PG8_SB(b, h) + boff + n * 2048 + k * 1024); } while (0)
; #define PG8_MMA(ai, bj, At, Bt) do { __builtin_amdgcn_s_setprio(1); _Pragma("unroll") for (int m = 0; m < 4; ++m) _Pragma("unroll") for (int n = 0; n < 2; ++n) _Pragma("unroll") for (int k = 0; k < 2; ++k) \
;         acc[ai][bj][m][n] = __builtin_amdgcn_mfma_f32_16x16x32_bf16(Bt[n][k], At[m][k], acc[ai][bj][m][n], 0, 0, 0); __builtin_amdgcn_s_setprio(0); } while (0)
; #define PG8_WAIT_L(n) asm volatile("s_waitcnt lgkmcnt(" #n ")" ::: "memory")
; #define PG8_BAR __builtin_amdgcn_s_barrier()
; template <class Epi, class Sched>
; __device__ __forceinline__ void gemm_phase(LAS unsigned char* lds, const Sched& S, const Epi& E) {
;     ...
;             const char* a1 = cA + (size_t)(t + 1) * kstep;
;             const char* a2 = last ? nA : cA + (size_t)(t + 2) * kstep; const char* b2 = last ? nB : cB + (size_t)(t + 2) * kstep;
;             const char* a3 = a2 + kstep; const char* b3 = b2 + kstep;
;             const unsigned xA0 = last ? nvA0 : vA0, xA1 = last ? nvA1 : vA1, xB0 = last ? nvB0 : vB0, xB1 = last ? nvB1 : vB1;
;             const size_t xhA = last ? nhA : hA, xhB = last ? nhB : hB;
;             PG8_LDB(B0, 0, 0); PG8_SCHED; PG8_LDA(At, 0, 0); PG8_STAGE(PG8_SA(1, 1), a1 + hA, vA0, vA1);
;             PG8_WAIT_L(8); PG8_BAR; PG8_WAIT_L(0); PG8_MMA(0, 0, At, B0); PG8_BAR; PG8_SCHED;
;             PG8_LDB(B1, 0, 1); PG8_STAGE(PG8_SB(0, 0), b2, xB0, xB1);
;             PG8_BAR; PG8_WAIT_L(0); PG8_MMA(0, 1, At, B1); PG8_BAR;
;             PG8_LDA(At, 0, 1); PG8_STAGE(PG8_SA(0, 0), a2, xA0, xA1);
;             PG8_BAR; PG8_WAIT_L(0); PG8_MMA(1, 0, At, B0); PG8_BAR; PG8_SCHED;
.LBB0_808:
	s_add_u32 s21, s26, 0xfff80080
	s_addc_u32 s69, s27, -1
	s_and_b64 s[40:41], exec, s[40:41]
	s_cselect_b32 s41, s23, s69
	s_cselect_b32 s40, s22, s21
	s_add_i32 s21, 0, 0x10000
	v_add_u32_e32 v138, s21, v155
	ds_read_b128 v[158:161], v138
	ds_read_b128 v[182:185], v138 offset:1024
	ds_read_b128 v[186:189], v138 offset:2048
	ds_read_b128 v[190:193], v138 offset:3072
	v_lshl_add_u64 v[138:139], s[26:27], 0, v[132:133]
	s_add_i32 m0, s48, 0xc000
	ds_read_b128 v[194:197], v143
	ds_read_b128 v[198:201], v143 offset:1024
	ds_read_b128 v[202:205], v143 offset:2048
	ds_read_b128 v[206:209], v143 offset:3072
	ds_read_b128 v[210:213], v143 offset:4096
	ds_read_b128 v[214:217], v143 offset:5120
	ds_read_b128 v[218:221], v143 offset:6144
	ds_read_b128 v[222:225], v143 offset:7168
	global_load_lds_dwordx4 v[138:139], off
	v_lshl_add_u64 v[138:139], s[26:27], 0, v[134:135]
	s_add_i32 m0, s48, 0xe000
	s_nop 0
	global_load_lds_dwordx4 v[138:139], off
	s_waitcnt lgkmcnt(8)
	s_barrier
	s_waitcnt lgkmcnt(0)
	s_setprio 1
	v_mfma_f32_16x16x32_bf16 v[124:127], v[158:161], v[194:197], v[124:127]
	v_mfma_f32_16x16x32_bf16 v[120:123], v[186:189], v[194:197], v[120:123]
	v_mfma_f32_16x16x32_bf16 v[112:115], v[158:161], v[202:205], v[112:115]
	v_mfma_f32_16x16x32_bf16 v[104:107], v[186:189], v[202:205], v[104:107]
	v_mfma_f32_16x16x32_bf16 v[96:99], v[158:161], v[210:213], v[96:99]
	v_mfma_f32_16x16x32_bf16 v[88:91], v[186:189], v[210:213], v[88:91]
	v_mfma_f32_16x16x32_bf16 v[80:83], v[158:161], v[218:221], v[80:83]
	v_mfma_f32_16x16x32_bf16 v[72:75], v[186:189], v[218:221], v[72:75]
	v_mfma_f32_16x16x32_bf16 v[124:127], v[182:185], v[198:201], v[124:127]
	v_mfma_f32_16x16x32_bf16 v[120:123], v[190:193], v[198:201], v[120:123]
	v_mfma_f32_16x16x32_bf16 v[112:115], v[182:185], v[206:209], v[112:115]
	v_mfma_f32_16x16x32_bf16 v[104:107], v[190:193], v[206:209], v[104:107]
	v_mfma_f32_16x16x32_bf16 v[96:99], v[182:185], v[214:217], v[96:99]
	v_mfma_f32_16x16x32_bf16 v[88:91], v[190:193], v[214:217], v[88:91]
	v_mfma_f32_16x16x32_bf16 v[80:83], v[182:185], v[222:225], v[80:83]
	v_mfma_f32_16x16x32_bf16 v[72:75], v[190:193], v[222:225], v[72:75]
	s_setprio 0
	s_barrier
	s_add_i32 s69, 0, 0x14000
	s_add_i32 s21, s21, s43
	v_add_u32_e32 v138, s69, v155
	s_mov_b32 m0, s21
	ds_read_b128 v[226:229], v138
	ds_read_b128 v[230:233], v138 offset:1024
	ds_read_b128 v[234:237], v138 offset:2048
	ds_read_b128 v[238:241], v138 offset:3072
	global_load_lds_dwordx4 v136, s[38:39]
	s_add_i32 m0, s21, 0x2000
	v_mov_b32_e32 v147, v137
	global_load_lds_dwordx4 v146, s[38:39]
	s_barrier
	s_waitcnt lgkmcnt(0)
	v_lshl_add_u64 v[138:139], s[38:39], 0, v[136:137]
	v_lshl_add_u64 v[140:141], s[38:39], 0, v[146:147]
	s_setprio 1
	v_mfma_f32_16x16x32_bf16 v[116:119], v[226:229], v[194:197], v[116:119]
	v_mfma_f32_16x16x32_bf16 v[108:111], v[234:237], v[194:197], v[108:111]
	v_mfma_f32_16x16x32_bf16 v[100:103], v[226:229], v[202:205], v[100:103]
	v_mfma_f32_16x16x32_bf16 v[92:95], v[234:237], v[202:205], v[92:95]
	v_mfma_f32_16x16x32_bf16 v[84:87], v[226:229], v[210:213], v[84:87]
	v_mfma_f32_16x16x32_bf16 v[76:79], v[234:237], v[210:213], v[76:79]
	v_mfma_f32_16x16x32_bf16 v[68:71], v[226:229], v[218:221], v[68:71]
	v_mfma_f32_16x16x32_bf16 v[64:67], v[234:237], v[218:221], v[64:67]
	v_mfma_f32_16x16x32_bf16 v[116:119], v[230:233], v[198:201], v[116:119]
	v_mfma_f32_16x16x32_bf16 v[108:111], v[238:241], v[198:201], v[108:111]
	v_mfma_f32_16x16x32_bf16 v[100:103], v[230:233], v[206:209], v[100:103]
	v_mfma_f32_16x16x32_bf16 v[92:95], v[238:241], v[206:209], v[92:95]
	v_mfma_f32_16x16x32_bf16 v[84:87], v[230:233], v[214:217], v[84:87]
	v_mfma_f32_16x16x32_bf16 v[76:79], v[238:241], v[214:217], v[76:79]
	v_mfma_f32_16x16x32_bf16 v[68:71], v[230:233], v[222:225], v[68:71]
	v_mfma_f32_16x16x32_bf16 v[64:67], v[238:241], v[222:225], v[64:67]
	s_setprio 0
	s_mov_b32 m0, s48
	v_lshl_add_u64 v[242:243], s[40:41], 0, v[150:151]
	s_barrier
	ds_read_b128 v[194:197], v143 offset:16384
	ds_read_b128 v[198:201], v143 offset:17408
	ds_read_b128 v[202:205], v143 offset:18432
	ds_read_b128 v[206:209], v143 offset:19456
	ds_read_b128 v[210:213], v143 offset:20480
	ds_read_b128 v[214:217], v143 offset:21504
	ds_read_b128 v[218:221], v143 offset:22528
	ds_read_b128 v[222:225], v143 offset:23552
	global_load_lds_dwordx4 v[242:243], off
	v_lshl_add_u64 v[244:245], s[40:41], 0, v[148:149]
	s_mov_b32 m0, s49
	s_nop 0
	global_load_lds_dwordx4 v[244:245], off
	s_barrier
	s_waitcnt lgkmcnt(0)
	s_setprio 1
	v_mfma_f32_16x16x32_bf16 v[60:63], v[158:161], v[194:197], v[60:63]
	v_mfma_f32_16x16x32_bf16 v[56:59], v[186:189], v[194:197], v[56:59]
	v_mfma_f32_16x16x32_bf16 v[44:47], v[158:161], v[202:205], v[44:47]
	v_mfma_f32_16x16x32_bf16 v[40:43], v[186:189], v[202:205], v[40:43]
	v_mfma_f32_16x16x32_bf16 v[28:31], v[158:161], v[210:213], v[28:31]
	v_mfma_f32_16x16x32_bf16 v[24:27], v[186:189], v[210:213], v[24:27]
	v_mfma_f32_16x16x32_bf16 v[12:15], v[158:161], v[218:221], v[12:15]
	v_mfma_f32_16x16x32_bf16 v[8:11], v[186:189], v[218:221], v[8:11]
	v_mfma_f32_16x16x32_bf16 v[60:63], v[182:185], v[198:201], v[60:63]
	v_mfma_f32_16x16x32_bf16 v[56:59], v[190:193], v[198:201], v[56:59]
	v_mfma_f32_16x16x32_bf16 v[44:47], v[182:185], v[206:209], v[44:47]
	v_mfma_f32_16x16x32_bf16 v[40:43], v[190:193], v[206:209], v[40:43]
	v_mfma_f32_16x16x32_bf16 v[28:31], v[182:185], v[214:217], v[28:31]
	v_mfma_f32_16x16x32_bf16 v[24:27], v[190:193], v[214:217], v[24:27]
	v_mfma_f32_16x16x32_bf16 v[12:15], v[182:185], v[222:225], v[12:15]
	v_mfma_f32_16x16x32_bf16 v[8:11], v[190:193], v[222:225], v[8:11]
	s_setprio 0
	s_barrier
; #define PG8_STAGE(bufoff, gbase, v0, v1) do { \
;         __builtin_amdgcn_global_load_lds((const unsigned*)((const char*)(gbase) + (v0)), (LAS unsigned*)(lds + (bufoff) + ldsw), 16, 0, 0); \
;         __builtin_amdgcn_global_load_lds((const unsigned*)((const char*)(gbase) + (v1)), (LAS unsigned*)(lds + (bufoff) + ldsw + 8192), 16, 0, 0); } while (0)
; #define PG8_LDA(dst, b, h) do { _Pragma("unroll") for (int m = 0; m < 4; ++m) _Pragma("unroll") for (int k = 0; k < 2; ++k) dst[m][k] = *(const LAS bf16x8*)(lds + PG8_SA(b, h) + aoff + m * 2048 + k * 1024); } while (0)
; #define PG8_LDB(dst, b, h) do { _Pragma("unroll") for (int n = 0; n < 2; ++n) _Pragma("unroll") for (int k = 0; k < 2; ++k) dst[n][k] = *(const LAS bf16x8*)(lds + PG8_SB(b, h) + boff + n * 2048 + k * 1024); } while (0)
; #define PG8_MMA(ai, bj, At, Bt) do { __builtin_amdgcn_s_setprio(1); _Pragma("unroll") for (int m = 0; m < 4; ++m) _Pragma("unroll") for (int n = 0; n < 2; ++n) _Pragma("unroll") for (int k = 0; k < 2; ++k) \
;         acc[ai][bj][m][n] = __builtin_amdgcn_mfma_f32_16x16x32_bf16(Bt[n][k], At[m][k], acc[ai][bj][m][n], 0, 0, 0); __builtin_amdgcn_s_setprio(0); } while (0)
; #define PG8_WAIT_V(n) asm volatile("s_waitcnt vmcnt(" #n ")" ::: "memory")
; #define PG8_WAIT_L(n) asm volatile("s_waitcnt lgkmcnt(" #n ")" ::: "memory")
; #define PG8_BAR __builtin_amdgcn_s_barrier()
; #define PG8_SCHED __builtin_amdgcn_sched_barrier(0)
; template <class Epi, class Sched>
; __device__ __forceinline__ void gemm_phase(LAS unsigned char* lds, const Sched& S, const Epi& E) {
;     ...
;             PG8_STAGE(PG8_SB(0, 1), b2 + xhB, xB0, xB1);
;             PG8_WAIT_V(6); PG8_BAR; PG8_MMA(1, 1, At, B1); PG8_BAR;
;             PG8_LDB(B0, 1, 0); PG8_SCHED; PG8_LDA(At, 1, 0); PG8_STAGE(PG8_SA(0, 1), a2 + xhA, xA0, xA1);
;             PG8_WAIT_L(8); PG8_BAR; PG8_WAIT_L(0); PG8_MMA(0, 0, At, B0); PG8_BAR; PG8_SCHED;
;             PG8_LDB(B1, 1, 1); PG8_STAGE(PG8_SB(1, 0), b3, xB0, xB1);
	s_add_u32 s70, s38, 0x80000
	s_addc_u32 s71, s39, 0
	s_add_i32 s21, s69, s43
	s_mov_b32 m0, s21
	s_nop 0
	global_load_lds_dwordx4 v136, s[70:71]
	s_add_i32 m0, s21, 0x2000
	s_nop 0
	global_load_lds_dwordx4 v146, s[70:71]
	s_waitcnt vmcnt(6)
	s_barrier
	s_setprio 1
	v_mfma_f32_16x16x32_bf16 v[52:55], v[226:229], v[194:197], v[52:55]
	v_mfma_f32_16x16x32_bf16 v[48:51], v[234:237], v[194:197], v[48:51]
	v_mfma_f32_16x16x32_bf16 v[36:39], v[226:229], v[202:205], v[36:39]
	v_mfma_f32_16x16x32_bf16 v[32:35], v[234:237], v[202:205], v[32:35]
	v_mfma_f32_16x16x32_bf16 v[20:23], v[226:229], v[210:213], v[20:23]
	v_mfma_f32_16x16x32_bf16 v[16:19], v[234:237], v[210:213], v[16:19]
	v_mfma_f32_16x16x32_bf16 v[4:7], v[226:229], v[218:221], v[4:7]
	v_mfma_f32_16x16x32_bf16 v[0:3], v[234:237], v[218:221], v[0:3]
	v_mfma_f32_16x16x32_bf16 v[52:55], v[230:233], v[198:201], v[52:55]
	v_mfma_f32_16x16x32_bf16 v[48:51], v[238:241], v[198:201], v[48:51]
	v_mfma_f32_16x16x32_bf16 v[36:39], v[230:233], v[206:209], v[36:39]
	v_mfma_f32_16x16x32_bf16 v[32:35], v[238:241], v[206:209], v[32:35]
	v_mfma_f32_16x16x32_bf16 v[20:23], v[230:233], v[214:217], v[20:23]
	v_mfma_f32_16x16x32_bf16 v[16:19], v[238:241], v[214:217], v[16:19]
	v_mfma_f32_16x16x32_bf16 v[4:7], v[230:233], v[222:225], v[4:7]
	v_mfma_f32_16x16x32_bf16 v[0:3], v[238:241], v[222:225], v[0:3]
	s_setprio 0
	s_add_i32 s21, 0, 0x18000
	v_add_u32_e32 v147, s21, v155
	s_barrier
	ds_read_b128 v[158:161], v147
	ds_read_b128 v[182:185], v147 offset:1024
	ds_read_b128 v[186:189], v147 offset:2048
	ds_read_b128 v[190:193], v147 offset:3072
	s_add_u32 s40, s40, 0x80000
	s_addc_u32 s41, s41, 0
	s_mov_b32 m0, s50
	v_lshl_add_u64 v[150:151], s[40:41], 0, v[150:151]
	ds_read_b128 v[194:197], v143 offset:32768
	ds_read_b128 v[198:201], v143 offset:33792
	ds_read_b128 v[202:205], v143 offset:34816
	ds_read_b128 v[206:209], v143 offset:35840
	ds_read_b128 v[210:213], v143 offset:36864
	ds_read_b128 v[214:217], v143 offset:37888
	ds_read_b128 v[218:221], v143 offset:38912
	ds_read_b128 v[222:225], v143 offset:39936
	global_load_lds_dwordx4 v[150:151], off
	v_lshl_add_u64 v[148:149], s[40:41], 0, v[148:149]
	s_mov_b32 m0, s51
	s_nop 0
	global_load_lds_dwordx4 v[148:149], off
	s_waitcnt lgkmcnt(8)
	s_barrier
	s_waitcnt lgkmcnt(0)
	s_setprio 1
	v_mfma_f32_16x16x32_bf16 v[124:127], v[158:161], v[194:197], v[124:127]
	v_mfma_f32_16x16x32_bf16 v[120:123], v[186:189], v[194:197], v[120:123]
	v_mfma_f32_16x16x32_bf16 v[112:115], v[158:161], v[202:205], v[112:115]
	v_mfma_f32_16x16x32_bf16 v[104:107], v[186:189], v[202:205], v[104:107]
	v_mfma_f32_16x16x32_bf16 v[96:99], v[158:161], v[210:213], v[96:99]
	v_mfma_f32_16x16x32_bf16 v[88:91], v[186:189], v[210:213], v[88:91]
	v_mfma_f32_16x16x32_bf16 v[80:83], v[158:161], v[218:221], v[80:83]
	v_mfma_f32_16x16x32_bf16 v[72:75], v[186:189], v[218:221], v[72:75]
	v_mfma_f32_16x16x32_bf16 v[124:127], v[182:185], v[198:201], v[124:127]
	v_mfma_f32_16x16x32_bf16 v[120:123], v[190:193], v[198:201], v[120:123]
	v_mfma_f32_16x16x32_bf16 v[112:115], v[182:185], v[206:209], v[112:115]
	v_mfma_f32_16x16x32_bf16 v[104:107], v[190:193], v[206:209], v[104:107]
	v_mfma_f32_16x16x32_bf16 v[96:99], v[182:185], v[214:217], v[96:99]
	v_mfma_f32_16x16x32_bf16 v[88:91], v[190:193], v[214:217], v[88:91]
	v_mfma_f32_16x16x32_bf16 v[80:83], v[182:185], v[222:225], v[80:83]
	v_mfma_f32_16x16x32_bf16 v[72:75], v[190:193], v[222:225], v[72:75]
	s_setprio 0
	s_barrier
	s_add_i32 s40, 0, 0x1c000
	s_add_i32 s21, s21, s43
	v_add_u32_e32 v147, s40, v155
	v_lshl_add_u64 v[138:139], v[138:139], 0, s[44:45]
	s_mov_b32 m0, s21
	ds_read_b128 v[148:151], v147
	ds_read_b128 v[226:229], v147 offset:1024
	ds_read_b128 v[230:233], v147 offset:2048
	ds_read_b128 v[234:237], v147 offset:3072
	global_load_lds_dwordx4 v[138:139], off
	v_lshl_add_u64 v[138:139], v[140:141], 0, s[44:45]
	s_add_i32 m0, s21, 0x2000
	s_nop 0
	global_load_lds_dwordx4 v[138:139], off
	s_barrier
; #define PG8_STAGE(bufoff, gbase, v0, v1) do { \
;         __builtin_amdgcn_global_load_lds((const unsigned*)((const char*)(gbase) + (v0)), (LAS unsigned*)(lds + (bufoff) + ldsw), 16, 0, 0); \
;         __builtin_amdgcn_global_load_lds((const unsigned*)((const char*)(gbase) + (v1)), (LAS unsigned*)(lds + (bufoff) + ldsw + 8192), 16, 0, 0); } while (0)
; #define PG8_LDA(dst, b, h) do { _Pragma("unroll") for (int m = 0; m < 4; ++m) _Pragma("unroll") for (int k = 0; k < 2; ++k) dst[m][k] = *(const LAS bf16x8*)(lds + PG8_SA(b, h) + aoff + m * 2048 + k * 1024); } while (0)
; #define PG8_MMA(ai, bj, At, Bt) do { __builtin_amdgcn_s_setprio(1); _Pragma("unroll") for (int m = 0; m < 4; ++m) _Pragma("unroll") for (int n = 0; n < 2; ++n) _Pragma("unroll") for (int k = 0; k < 2; ++k) \
;         acc[ai][bj][m][n] = __builtin_amdgcn_mfma_f32_16x16x32_bf16(Bt[n][k], At[m][k], acc[ai][bj][m][n], 0, 0, 0); __builtin_amdgcn_s_setprio(0); } while (0)
; #define PG8_WAIT_V(n) asm volatile("s_waitcnt vmcnt(" #n ")" ::: "memory")
; #define PG8_WAIT_L(n) asm volatile("s_waitcnt lgkmcnt(" #n ")" ::: "memory")
; #define PG8_BAR __builtin_amdgcn_s_barrier()
; #define PG8_SCHED __builtin_amdgcn_sched_barrier(0)
; template <class Epi, class Sched>
; __device__ __forceinline__ void gemm_phase(LAS unsigned char* lds, const Sched& S, const Epi& E) {
;     ...
;         for (int t = 0; t < nt; t += 2) {
;             const bool last = (t == nt - 2);
;             const char* a1 = cA + (size_t)(t + 1) * kstep;
;             const char* a2 = last ? nA : cA + (size_t)(t + 2) * kstep; const char* b2 = last ? nB : cB + (size_t)(t + 2) * kstep;
;             const char* a3 = a2 + kstep; const char* b3 = b2 + kstep;
;             const unsigned xA0 = last ? nvA0 : vA0, xA1 = last ? nvA1 : vA1, xB0 = last ? nvB0 : vB0, xB1 = last ? nvB1 : vB1;
;             const size_t xhA = last ? nhA : hA, xhB = last ? nhB : hB;
;     ...
;             PG8_BAR; PG8_WAIT_L(0); PG8_MMA(0, 1, At, B1); PG8_BAR;
;             PG8_LDA(At, 1, 1); PG8_STAGE(PG8_SA(1, 0), a3, xA0, xA1);
;             PG8_BAR; PG8_WAIT_L(0); PG8_MMA(1, 0, At, B0); PG8_BAR; PG8_SCHED;
;             PG8_STAGE(PG8_SB(1, 1), b3 + xhB, xB0, xB1);
;             PG8_WAIT_V(6); PG8_BAR; PG8_MMA(1, 1, At, B1); PG8_BAR;
	s_waitcnt lgkmcnt(0)
	s_setprio 1
	v_mfma_f32_16x16x32_bf16 v[116:119], v[148:151], v[194:197], v[116:119]
	v_mfma_f32_16x16x32_bf16 v[108:111], v[230:233], v[194:197], v[108:111]
	v_mfma_f32_16x16x32_bf16 v[100:103], v[148:151], v[202:205], v[100:103]
	v_mfma_f32_16x16x32_bf16 v[92:95], v[230:233], v[202:205], v[92:95]
	v_mfma_f32_16x16x32_bf16 v[84:87], v[148:151], v[210:213], v[84:87]
	v_mfma_f32_16x16x32_bf16 v[76:79], v[230:233], v[210:213], v[76:79]
	v_mfma_f32_16x16x32_bf16 v[68:71], v[148:151], v[218:221], v[68:71]
	v_mfma_f32_16x16x32_bf16 v[64:67], v[230:233], v[218:221], v[64:67]
	v_mfma_f32_16x16x32_bf16 v[116:119], v[226:229], v[198:201], v[116:119]
	v_mfma_f32_16x16x32_bf16 v[108:111], v[234:237], v[198:201], v[108:111]
	v_mfma_f32_16x16x32_bf16 v[100:103], v[226:229], v[206:209], v[100:103]
	v_mfma_f32_16x16x32_bf16 v[92:95], v[234:237], v[206:209], v[92:95]
	v_mfma_f32_16x16x32_bf16 v[84:87], v[226:229], v[214:217], v[84:87]
	v_mfma_f32_16x16x32_bf16 v[76:79], v[234:237], v[214:217], v[76:79]
	v_mfma_f32_16x16x32_bf16 v[68:71], v[226:229], v[222:225], v[68:71]
	v_mfma_f32_16x16x32_bf16 v[64:67], v[234:237], v[222:225], v[64:67]
	s_setprio 0
	s_mov_b32 m0, s64
	v_lshl_add_u64 v[138:139], v[242:243], 0, s[44:45]
	s_barrier
	ds_read_b128 v[194:197], v143 offset:49152
	ds_read_b128 v[198:201], v143 offset:50176
	ds_read_b128 v[202:205], v143 offset:51200
	ds_read_b128 v[206:209], v143 offset:52224
	ds_read_b128 v[210:213], v143 offset:53248
	ds_read_b128 v[214:217], v143 offset:54272
	ds_read_b128 v[218:221], v143 offset:55296
	ds_read_b128 v[222:225], v143 offset:56320
	global_load_lds_dwordx4 v[138:139], off
	v_lshl_add_u64 v[138:139], v[244:245], 0, s[44:45]
	s_mov_b32 m0, s65
	s_nop 0
	global_load_lds_dwordx4 v[138:139], off
	s_barrier
	s_waitcnt lgkmcnt(0)
	s_setprio 1
	v_mfma_f32_16x16x32_bf16 v[60:63], v[158:161], v[194:197], v[60:63]
	v_mfma_f32_16x16x32_bf16 v[56:59], v[186:189], v[194:197], v[56:59]
	v_mfma_f32_16x16x32_bf16 v[44:47], v[158:161], v[202:205], v[44:47]
	v_mfma_f32_16x16x32_bf16 v[40:43], v[186:189], v[202:205], v[40:43]
	v_mfma_f32_16x16x32_bf16 v[28:31], v[158:161], v[210:213], v[28:31]
	v_mfma_f32_16x16x32_bf16 v[24:27], v[186:189], v[210:213], v[24:27]
	v_mfma_f32_16x16x32_bf16 v[12:15], v[158:161], v[218:221], v[12:15]
	v_mfma_f32_16x16x32_bf16 v[8:11], v[186:189], v[218:221], v[8:11]
	v_mfma_f32_16x16x32_bf16 v[60:63], v[182:185], v[198:201], v[60:63]
	v_mfma_f32_16x16x32_bf16 v[56:59], v[190:193], v[198:201], v[56:59]
	v_mfma_f32_16x16x32_bf16 v[44:47], v[182:185], v[206:209], v[44:47]
	v_mfma_f32_16x16x32_bf16 v[40:43], v[190:193], v[206:209], v[40:43]
	v_mfma_f32_16x16x32_bf16 v[28:31], v[182:185], v[214:217], v[28:31]
	v_mfma_f32_16x16x32_bf16 v[24:27], v[190:193], v[214:217], v[24:27]
	v_mfma_f32_16x16x32_bf16 v[12:15], v[182:185], v[222:225], v[12:15]
	v_mfma_f32_16x16x32_bf16 v[8:11], v[190:193], v[222:225], v[8:11]
	s_setprio 0
	s_barrier
	s_add_u32 s38, s38, 0x80080
	s_addc_u32 s39, s39, 0
	s_add_i32 s21, s40, s43
	s_mov_b32 m0, s21
	s_nop 0
	global_load_lds_dwordx4 v136, s[38:39]
	s_add_i32 m0, s21, 0x2000
	s_nop 0
	global_load_lds_dwordx4 v146, s[38:39]
	s_waitcnt vmcnt(6)
	s_barrier
	s_setprio 1
	v_mfma_f32_16x16x32_bf16 v[52:55], v[148:151], v[194:197], v[52:55]
	v_mfma_f32_16x16x32_bf16 v[48:51], v[230:233], v[194:197], v[48:51]
	v_mfma_f32_16x16x32_bf16 v[36:39], v[148:151], v[202:205], v[36:39]
	v_mfma_f32_16x16x32_bf16 v[32:35], v[230:233], v[202:205], v[32:35]
	v_mfma_f32_16x16x32_bf16 v[20:23], v[148:151], v[210:213], v[20:23]
	v_mfma_f32_16x16x32_bf16 v[16:19], v[230:233], v[210:213], v[16:19]
	v_mfma_f32_16x16x32_bf16 v[4:7], v[148:151], v[218:221], v[4:7]
	v_mfma_f32_16x16x32_bf16 v[0:3], v[230:233], v[218:221], v[0:3]
	v_mfma_f32_16x16x32_bf16 v[52:55], v[226:229], v[198:201], v[52:55]
	v_mfma_f32_16x16x32_bf16 v[48:51], v[234:237], v[198:201], v[48:51]
	v_mfma_f32_16x16x32_bf16 v[36:39], v[226:229], v[206:209], v[36:39]
	v_mfma_f32_16x16x32_bf16 v[32:35], v[234:237], v[206:209], v[32:35]
	v_mfma_f32_16x16x32_bf16 v[20:23], v[226:229], v[214:217], v[20:23]
	v_mfma_f32_16x16x32_bf16 v[16:19], v[234:237], v[214:217], v[16:19]
	v_mfma_f32_16x16x32_bf16 v[4:7], v[226:229], v[222:225], v[4:7]
	v_mfma_f32_16x16x32_bf16 v[0:3], v[234:237], v[222:225], v[0:3]
	s_setprio 0
	s_add_i32 s15, s15, 2
	s_add_u32 s26, s26, 0x100
	s_addc_u32 s27, s27, 0
	s_add_u32 s34, s34, 0x100
	s_addc_u32 s35, s35, 0
	s_cmp_gt_u32 s15, 29
	s_cbranch_scc1 .Lrot_exit_3
	s_cmp_eq_u32 s15, 28
	s_cselect_b64 s[40:41], -1, 0
	s_and_b64 vcc, exec, s[40:41]
	v_mov_b64_e32 v[148:149], v[130:131]
	v_mov_b64_e32 v[150:151], v[128:129]
	v_mov_b32_e32 v146, v156
	v_mov_b32_e32 v136, v145
	s_mov_b64 s[38:39], s[24:25]
	s_cbranch_vccnz .Lrot_join_3
	v_mov_b64_e32 v[148:149], v[134:135]
	v_mov_b64_e32 v[150:151], v[132:133]
	v_mov_b32_e32 v146, v142
	v_mov_b32_e32 v136, v144
	s_mov_b64 s[38:39], s[34:35]

; #define PG8_STAGE(bufoff, gbase, v0, v1) do { \
;         __builtin_amdgcn_global_load_lds((const unsigned*)((const char*)(gbase) + (v0)), (LAS unsigned*)(lds + (bufoff) + ldsw), 16, 0, 0); \
;         __builtin_amdgcn_global_load_lds((const unsigned*)((const char*)(gbase) + (v1)), (LAS unsigned*)(lds + (bufoff) + ldsw + 8192), 16, 0, 0); } while (0)
; #define PG8_LDA(dst, b, h) do { _Pragma("unroll") for (int m = 0; m < 4; ++m) _Pragma("unroll") for (int k = 0; k < 2; ++k) dst[m][k] = *(const LAS bf16x8*)(lds + PG8_SA(b, h) + aoff + m * 2048 + k * 1024); } while (0)
; #define PG8_LDB(dst, b, h) do { _Pragma("unroll") for (int n = 0; n < 2; ++n) _Pragma("unroll") for (int k = 0; k < 2; ++k) dst[n][k] = *(const LAS bf16x8*)(lds + PG8_SB(b, h) + boff + n * 2048 + k * 1024); } while (0)
; #define PG8_MMA(ai, bj, At, Bt) do { __builtin_amdgcn_s_setprio(1); _Pragma("unroll") for (int m = 0; m < 4; ++m) _Pragma("unroll") for (int n = 0; n < 2; ++n) _Pragma("unroll") for (int k = 0; k < 2; ++k) \
;         acc[ai][bj][m][n] = __builtin_amdgcn_mfma_f32_16x16x32_bf16(Bt[n][k], At[m][k], acc[ai][bj][m][n], 0, 0, 0); __builtin_amdgcn_s_setprio(0); } while (0)
; #define PG8_WAIT_L(n) asm volatile("s_waitcnt lgkmcnt(" #n ")" ::: "memory")
; #define PG8_BAR __builtin_amdgcn_s_barrier()
; template <class Epi, class Sched>
; __device__ __forceinline__ void gemm_phase(LAS unsigned char* lds, const Sched& S, const Epi& E) {
;     ...
;             const char* a1 = cA + (size_t)(t + 1) * kstep;
;             const char* a2 = last ? nA : cA + (size_t)(t + 2) * kstep; const char* b2 = last ? nB : cB + (size_t)(t + 2) * kstep;
;             const char* a3 = a2 + kstep; const char* b3 = b2 + kstep;
;             const unsigned xA0 = last ? nvA0 : vA0, xA1 = last ? nvA1 : vA1, xB0 = last ? nvB0 : vB0, xB1 = last ? nvB1 : vB1;
;             const size_t xhA = last ? nhA : hA, xhB = last ? nhB : hB;
;             PG8_LDB(B0, 0, 0); PG8_SCHED; PG8_LDA(At, 0, 0); PG8_STAGE(PG8_SA(1, 1), a1 + hA, vA0, vA1);
;             PG8_WAIT_L(8); PG8_BAR; PG8_WAIT_L(0); PG8_MMA(0, 0, At, B0); PG8_BAR; PG8_SCHED;
;             PG8_LDB(B1, 0, 1); PG8_STAGE(PG8_SB(0, 0), b2, xB0, xB1);
;             PG8_BAR; PG8_WAIT_L(0); PG8_MMA(0, 1, At, B1); PG8_BAR;
;             PG8_LDA(At, 0, 1); PG8_STAGE(PG8_SA(0, 0), a2, xA0, xA1);
;             PG8_BAR; PG8_WAIT_L(0); PG8_MMA(1, 0, At, B0); PG8_BAR; PG8_SCHED;
.LBB0_847:
	s_add_u32 s15, s24, 0xffe00080
	s_addc_u32 s70, s25, -1
	s_and_b64 s[38:39], exec, s[38:39]
	s_cselect_b32 s39, s21, s70
	s_cselect_b32 s38, s20, s15
	s_add_i32 s15, 0, 0x10000
	v_add_u32_e32 v138, s15, v147
	ds_read_b128 v[150:153], v138
	ds_read_b128 v[154:157], v138 offset:1024
	ds_read_b128 v[158:161], v138 offset:2048
	ds_read_b128 v[182:185], v138 offset:3072
	v_lshl_add_u64 v[138:139], s[24:25], 0, v[136:137]
	s_add_i32 m0, s49, 0xc000
	ds_read_b128 v[186:189], v148
	ds_read_b128 v[190:193], v148 offset:1024
	ds_read_b128 v[194:197], v148 offset:2048
	ds_read_b128 v[198:201], v148 offset:3072
	ds_read_b128 v[202:205], v148 offset:4096
	ds_read_b128 v[206:209], v148 offset:5120
	ds_read_b128 v[210:213], v148 offset:6144
	ds_read_b128 v[214:217], v148 offset:7168
	global_load_lds_dwordx4 v[138:139], off
	v_lshl_add_u64 v[138:139], s[24:25], 0, v[132:133]
	s_add_i32 m0, s49, 0xe000
	s_nop 0
	global_load_lds_dwordx4 v[138:139], off
	s_waitcnt lgkmcnt(8)
	s_barrier
	s_waitcnt lgkmcnt(0)
	s_setprio 1
	v_mfma_f32_16x16x32_bf16 v[124:127], v[150:153], v[186:189], v[124:127]
	v_mfma_f32_16x16x32_bf16 v[120:123], v[158:161], v[186:189], v[120:123]
	v_mfma_f32_16x16x32_bf16 v[108:111], v[150:153], v[194:197], v[108:111]
	v_mfma_f32_16x16x32_bf16 v[104:107], v[158:161], v[194:197], v[104:107]
	v_mfma_f32_16x16x32_bf16 v[100:103], v[150:153], v[202:205], v[100:103]
	v_mfma_f32_16x16x32_bf16 v[96:99], v[158:161], v[202:205], v[96:99]
	v_mfma_f32_16x16x32_bf16 v[84:87], v[150:153], v[210:213], v[84:87]
	v_mfma_f32_16x16x32_bf16 v[80:83], v[158:161], v[210:213], v[80:83]
	v_mfma_f32_16x16x32_bf16 v[124:127], v[154:157], v[190:193], v[124:127]
	v_mfma_f32_16x16x32_bf16 v[120:123], v[182:185], v[190:193], v[120:123]
	v_mfma_f32_16x16x32_bf16 v[108:111], v[154:157], v[198:201], v[108:111]
	v_mfma_f32_16x16x32_bf16 v[104:107], v[182:185], v[198:201], v[104:107]
	v_mfma_f32_16x16x32_bf16 v[100:103], v[154:157], v[206:209], v[100:103]
	v_mfma_f32_16x16x32_bf16 v[96:99], v[182:185], v[206:209], v[96:99]
	v_mfma_f32_16x16x32_bf16 v[84:87], v[154:157], v[214:217], v[84:87]
	v_mfma_f32_16x16x32_bf16 v[80:83], v[182:185], v[214:217], v[80:83]
	s_setprio 0
	s_barrier
	s_add_i32 s82, 0, 0x14000
	v_add_u32_e32 v138, s82, v147
	s_add_i32 s15, s15, s48
	ds_read_b128 v[218:221], v138
	ds_read_b128 v[222:225], v138 offset:1024
	ds_read_b128 v[226:229], v138 offset:2048
	ds_read_b128 v[230:233], v138 offset:3072
	v_lshl_add_u64 v[138:139], s[34:35], 0, v[142:143]
	s_mov_b32 m0, s15
	v_lshl_add_u64 v[140:141], s[34:35], 0, v[134:135]
	global_load_lds_dwordx4 v[138:139], off
	s_add_i32 m0, s15, 0x2000
	s_nop 0
	global_load_lds_dwordx4 v[140:141], off
	s_barrier
	s_waitcnt lgkmcnt(0)
	s_setprio 1
	v_mfma_f32_16x16x32_bf16 v[116:119], v[218:221], v[186:189], v[116:119]
	v_mfma_f32_16x16x32_bf16 v[112:115], v[226:229], v[186:189], v[112:115]
	v_mfma_f32_16x16x32_bf16 v[92:95], v[218:221], v[194:197], v[92:95]
	v_mfma_f32_16x16x32_bf16 v[88:91], v[226:229], v[194:197], v[88:91]
	v_mfma_f32_16x16x32_bf16 v[76:79], v[218:221], v[202:205], v[76:79]
	v_mfma_f32_16x16x32_bf16 v[72:75], v[226:229], v[202:205], v[72:75]
	v_mfma_f32_16x16x32_bf16 v[68:71], v[218:221], v[210:213], v[68:71]
	v_mfma_f32_16x16x32_bf16 v[64:67], v[226:229], v[210:213], v[64:67]
	v_mfma_f32_16x16x32_bf16 v[116:119], v[222:225], v[190:193], v[116:119]
	v_mfma_f32_16x16x32_bf16 v[112:115], v[230:233], v[190:193], v[112:115]
	v_mfma_f32_16x16x32_bf16 v[92:95], v[222:225], v[198:201], v[92:95]
	v_mfma_f32_16x16x32_bf16 v[88:91], v[230:233], v[198:201], v[88:91]
	v_mfma_f32_16x16x32_bf16 v[76:79], v[222:225], v[206:209], v[76:79]
	v_mfma_f32_16x16x32_bf16 v[72:75], v[230:233], v[206:209], v[72:75]
	v_mfma_f32_16x16x32_bf16 v[68:71], v[222:225], v[214:217], v[68:71]
	v_mfma_f32_16x16x32_bf16 v[64:67], v[230:233], v[214:217], v[64:67]
	s_setprio 0
	s_mov_b32 m0, s49
	v_lshl_add_u64 v[234:235], s[38:39], 0, v[142:143]
	s_barrier
	ds_read_b128 v[186:189], v148 offset:16384
	ds_read_b128 v[190:193], v148 offset:17408
	ds_read_b128 v[194:197], v148 offset:18432
	ds_read_b128 v[198:201], v148 offset:19456
	ds_read_b128 v[202:205], v148 offset:20480
	ds_read_b128 v[206:209], v148 offset:21504
	ds_read_b128 v[210:213], v148 offset:22528
	ds_read_b128 v[214:217], v148 offset:23552
	global_load_lds_dwordx4 v[234:235], off
	v_lshl_add_u64 v[236:237], s[38:39], 0, v[134:135]
	s_mov_b32 m0, s50
	s_nop 0
	global_load_lds_dwordx4 v[236:237], off
	s_barrier
	s_waitcnt lgkmcnt(0)
	s_setprio 1
	v_mfma_f32_16x16x32_bf16 v[60:63], v[150:153], v[186:189], v[60:63]
	v_mfma_f32_16x16x32_bf16 v[56:59], v[158:161], v[186:189], v[56:59]
	v_mfma_f32_16x16x32_bf16 v[44:47], v[150:153], v[194:197], v[44:47]
	v_mfma_f32_16x16x32_bf16 v[40:43], v[158:161], v[194:197], v[40:43]
	v_mfma_f32_16x16x32_bf16 v[28:31], v[150:153], v[202:205], v[28:31]
	v_mfma_f32_16x16x32_bf16 v[24:27], v[158:161], v[202:205], v[24:27]
	v_mfma_f32_16x16x32_bf16 v[12:15], v[150:153], v[210:213], v[12:15]
	v_mfma_f32_16x16x32_bf16 v[8:11], v[158:161], v[210:213], v[8:11]
	v_mfma_f32_16x16x32_bf16 v[60:63], v[154:157], v[190:193], v[60:63]
	v_mfma_f32_16x16x32_bf16 v[56:59], v[182:185], v[190:193], v[56:59]
	v_mfma_f32_16x16x32_bf16 v[44:47], v[154:157], v[198:201], v[44:47]
	v_mfma_f32_16x16x32_bf16 v[40:43], v[182:185], v[198:201], v[40:43]
	v_mfma_f32_16x16x32_bf16 v[28:31], v[154:157], v[206:209], v[28:31]
	v_mfma_f32_16x16x32_bf16 v[24:27], v[182:185], v[206:209], v[24:27]
	v_mfma_f32_16x16x32_bf16 v[12:15], v[154:157], v[214:217], v[12:15]
	v_mfma_f32_16x16x32_bf16 v[8:11], v[182:185], v[214:217], v[8:11]
	s_setprio 0
	s_barrier
; #define PG8_STAGE(bufoff, gbase, v0, v1) do { \
;         __builtin_amdgcn_global_load_lds((const unsigned*)((const char*)(gbase) + (v0)), (LAS unsigned*)(lds + (bufoff) + ldsw), 16, 0, 0); \
;         __builtin_amdgcn_global_load_lds((const unsigned*)((const char*)(gbase) + (v1)), (LAS unsigned*)(lds + (bufoff) + ldsw + 8192), 16, 0, 0); } while (0)
; #define PG8_LDA(dst, b, h) do { _Pragma("unroll") for (int m = 0; m < 4; ++m) _Pragma("unroll") for (int k = 0; k < 2; ++k) dst[m][k] = *(const LAS bf16x8*)(lds + PG8_SA(b, h) + aoff + m * 2048 + k * 1024); } while (0)
; #define PG8_LDB(dst, b, h) do { _Pragma("unroll") for (int n = 0; n < 2; ++n) _Pragma("unroll") for (int k = 0; k < 2; ++k) dst[n][k] = *(const LAS bf16x8*)(lds + PG8_SB(b, h) + boff + n * 2048 + k * 1024); } while (0)
; #define PG8_MMA(ai, bj, At, Bt) do { __builtin_amdgcn_s_setprio(1); _Pragma("unroll") for (int m = 0; m < 4; ++m) _Pragma("unroll") for (int n = 0; n < 2; ++n) _Pragma("unroll") for (int k = 0; k < 2; ++k) \
;         acc[ai][bj][m][n] = __builtin_amdgcn_mfma_f32_16x16x32_bf16(Bt[n][k], At[m][k], acc[ai][bj][m][n], 0, 0, 0); __builtin_amdgcn_s_setprio(0); } while (0)
; #define PG8_WAIT_V(n) asm volatile("s_waitcnt vmcnt(" #n ")" ::: "memory")
; #define PG8_WAIT_L(n) asm volatile("s_waitcnt lgkmcnt(" #n ")" ::: "memory")
; #define PG8_BAR __builtin_amdgcn_s_barrier()
; #define PG8_SCHED __builtin_amdgcn_sched_barrier(0)
; template <class Epi, class Sched>
; __device__ __forceinline__ void gemm_phase(LAS unsigned char* lds, const Sched& S, const Epi& E) {
;     ...
;             PG8_STAGE(PG8_SB(0, 1), b2 + xhB, xB0, xB1);
;             PG8_WAIT_V(6); PG8_BAR; PG8_MMA(1, 1, At, B1); PG8_BAR;
;             PG8_LDB(B0, 1, 0); PG8_SCHED; PG8_LDA(At, 1, 0); PG8_STAGE(PG8_SA(0, 1), a2 + xhA, xA0, xA1);
;             PG8_WAIT_L(8); PG8_BAR; PG8_WAIT_L(0); PG8_MMA(0, 0, At, B0); PG8_BAR; PG8_SCHED;
;             PG8_LDB(B1, 1, 1); PG8_STAGE(PG8_SB(1, 0), b3, xB0, xB1);
	s_add_u32 s70, s34, 0x200000
	s_addc_u32 s71, s35, 0
	s_add_i32 s15, s82, s48
	v_lshl_add_u64 v[150:151], s[70:71], 0, v[142:143]
	s_mov_b32 m0, s15
	s_nop 0
	global_load_lds_dwordx4 v[150:151], off
	v_lshl_add_u64 v[150:151], s[70:71], 0, v[134:135]
	s_add_i32 m0, s15, 0x2000
	s_nop 0
	global_load_lds_dwordx4 v[150:151], off
	s_waitcnt vmcnt(6)
	s_barrier
	s_setprio 1
	v_mfma_f32_16x16x32_bf16 v[52:55], v[218:221], v[186:189], v[52:55]
	v_mfma_f32_16x16x32_bf16 v[48:51], v[226:229], v[186:189], v[48:51]
	v_mfma_f32_16x16x32_bf16 v[36:39], v[218:221], v[194:197], v[36:39]
	v_mfma_f32_16x16x32_bf16 v[32:35], v[226:229], v[194:197], v[32:35]
	v_mfma_f32_16x16x32_bf16 v[20:23], v[218:221], v[202:205], v[20:23]
	v_mfma_f32_16x16x32_bf16 v[16:19], v[226:229], v[202:205], v[16:19]
	v_mfma_f32_16x16x32_bf16 v[4:7], v[218:221], v[210:213], v[4:7]
	v_mfma_f32_16x16x32_bf16 v[0:3], v[226:229], v[210:213], v[0:3]
	v_mfma_f32_16x16x32_bf16 v[52:55], v[222:225], v[190:193], v[52:55]
	v_mfma_f32_16x16x32_bf16 v[48:51], v[230:233], v[190:193], v[48:51]
	v_mfma_f32_16x16x32_bf16 v[36:39], v[222:225], v[198:201], v[36:39]
	v_mfma_f32_16x16x32_bf16 v[32:35], v[230:233], v[198:201], v[32:35]
	v_mfma_f32_16x16x32_bf16 v[20:23], v[222:225], v[206:209], v[20:23]
	v_mfma_f32_16x16x32_bf16 v[16:19], v[230:233], v[206:209], v[16:19]
	v_mfma_f32_16x16x32_bf16 v[4:7], v[222:225], v[214:217], v[4:7]
	v_mfma_f32_16x16x32_bf16 v[0:3], v[230:233], v[214:217], v[0:3]
	s_setprio 0
	s_add_i32 s15, 0, 0x18000
	v_add_u32_e32 v149, s15, v147
	s_barrier
	ds_read_b128 v[150:153], v149
	ds_read_b128 v[154:157], v149 offset:1024
	ds_read_b128 v[158:161], v149 offset:2048
	ds_read_b128 v[182:185], v149 offset:3072
	s_add_u32 s38, s38, 0x200000
	s_addc_u32 s39, s39, 0
	s_mov_b32 m0, s51
	v_lshl_add_u64 v[218:219], s[38:39], 0, v[142:143]
	ds_read_b128 v[186:189], v148 offset:32768
	ds_read_b128 v[190:193], v148 offset:33792
	ds_read_b128 v[194:197], v148 offset:34816
	ds_read_b128 v[198:201], v148 offset:35840
	ds_read_b128 v[202:205], v148 offset:36864
	ds_read_b128 v[206:209], v148 offset:37888
	ds_read_b128 v[210:213], v148 offset:38912
	ds_read_b128 v[214:217], v148 offset:39936
	global_load_lds_dwordx4 v[218:219], off
	v_lshl_add_u64 v[218:219], s[38:39], 0, v[134:135]
	s_mov_b32 m0, s54
	s_nop 0
	global_load_lds_dwordx4 v[218:219], off
	s_waitcnt lgkmcnt(8)
	s_barrier
	s_waitcnt lgkmcnt(0)
	s_setprio 1
	v_mfma_f32_16x16x32_bf16 v[124:127], v[150:153], v[186:189], v[124:127]
	v_mfma_f32_16x16x32_bf16 v[120:123], v[158:161], v[186:189], v[120:123]
	v_mfma_f32_16x16x32_bf16 v[108:111], v[150:153], v[194:197], v[108:111]
	v_mfma_f32_16x16x32_bf16 v[104:107], v[158:161], v[194:197], v[104:107]
	v_mfma_f32_16x16x32_bf16 v[100:103], v[150:153], v[202:205], v[100:103]
	v_mfma_f32_16x16x32_bf16 v[96:99], v[158:161], v[202:205], v[96:99]
	v_mfma_f32_16x16x32_bf16 v[84:87], v[150:153], v[210:213], v[84:87]
	v_mfma_f32_16x16x32_bf16 v[80:83], v[158:161], v[210:213], v[80:83]
	v_mfma_f32_16x16x32_bf16 v[124:127], v[154:157], v[190:193], v[124:127]
	v_mfma_f32_16x16x32_bf16 v[120:123], v[182:185], v[190:193], v[120:123]
	v_mfma_f32_16x16x32_bf16 v[108:111], v[154:157], v[198:201], v[108:111]
	v_mfma_f32_16x16x32_bf16 v[104:107], v[182:185], v[198:201], v[104:107]
	v_mfma_f32_16x16x32_bf16 v[100:103], v[154:157], v[206:209], v[100:103]
	v_mfma_f32_16x16x32_bf16 v[96:99], v[182:185], v[206:209], v[96:99]
	v_mfma_f32_16x16x32_bf16 v[84:87], v[154:157], v[214:217], v[84:87]
	v_mfma_f32_16x16x32_bf16 v[80:83], v[182:185], v[214:217], v[80:83]
	s_setprio 0
	s_barrier
	s_add_i32 s38, 0, 0x1c000
	s_add_i32 s15, s15, s48
	v_add_u32_e32 v149, s38, v147
	v_lshl_add_u64 v[138:139], v[138:139], 0, s[44:45]
	s_mov_b32 m0, s15
	ds_read_b128 v[218:221], v149
	ds_read_b128 v[222:225], v149 offset:1024
	ds_read_b128 v[226:229], v149 offset:2048
	ds_read_b128 v[230:233], v149 offset:3072
	global_load_lds_dwordx4 v[138:139], off
	v_lshl_add_u64 v[138:139], v[140:141], 0, s[44:45]
	s_add_i32 m0, s15, 0x2000
	s_nop 0
	global_load_lds_dwordx4 v[138:139], off
	s_barrier
; #define PG8_STAGE(bufoff, gbase, v0, v1) do { \
;         __builtin_amdgcn_global_load_lds((const unsigned*)((const char*)(gbase) + (v0)), (LAS unsigned*)(lds + (bufoff) + ldsw), 16, 0, 0); \
;         __builtin_amdgcn_global_load_lds((const unsigned*)((const char*)(gbase) + (v1)), (LAS unsigned*)(lds + (bufoff) + ldsw + 8192), 16, 0, 0); } while (0)
; #define PG8_LDA(dst, b, h) do { _Pragma("unroll") for (int m = 0; m < 4; ++m) _Pragma("unroll") for (int k = 0; k < 2; ++k) dst[m][k] = *(const LAS bf16x8*)(lds + PG8_SA(b, h) + aoff + m * 2048 + k * 1024); } while (0)
; #define PG8_MMA(ai, bj, At, Bt) do { __builtin_amdgcn_s_setprio(1); _Pragma("unroll") for (int m = 0; m < 4; ++m) _Pragma("unroll") for (int n = 0; n < 2; ++n) _Pragma("unroll") for (int k = 0; k < 2; ++k) \
;         acc[ai][bj][m][n] = __builtin_amdgcn_mfma_f32_16x16x32_bf16(Bt[n][k], At[m][k], acc[ai][bj][m][n], 0, 0, 0); __builtin_amdgcn_s_setprio(0); } while (0)
; #define PG8_WAIT_V(n) asm volatile("s_waitcnt vmcnt(" #n ")" ::: "memory")
; #define PG8_WAIT_L(n) asm volatile("s_waitcnt lgkmcnt(" #n ")" ::: "memory")
; #define PG8_BAR __builtin_amdgcn_s_barrier()
; #define PG8_SCHED __builtin_amdgcn_sched_barrier(0)
; template <class Epi, class Sched>
; __device__ __forceinline__ void gemm_phase(LAS unsigned char* lds, const Sched& S, const Epi& E) {
;     ...
;         for (int t = 0; t < nt; t += 2) {
;             const bool last = (t == nt - 2);
;             const char* a1 = cA + (size_t)(t + 1) * kstep;
;             const char* a2 = last ? nA : cA + (size_t)(t + 2) * kstep; const char* b2 = last ? nB : cB + (size_t)(t + 2) * kstep;
;             const char* a3 = a2 + kstep; const char* b3 = b2 + kstep;
;             const unsigned xA0 = last ? nvA0 : vA0, xA1 = last ? nvA1 : vA1, xB0 = last ? nvB0 : vB0, xB1 = last ? nvB1 : vB1;
;             const size_t xhA = last ? nhA : hA, xhB = last ? nhB : hB;
;     ...
;             PG8_BAR; PG8_WAIT_L(0); PG8_MMA(0, 1, At, B1); PG8_BAR;
;             PG8_LDA(At, 1, 1); PG8_STAGE(PG8_SA(1, 0), a3, xA0, xA1);
;             PG8_BAR; PG8_WAIT_L(0); PG8_MMA(1, 0, At, B0); PG8_BAR; PG8_SCHED;
;             PG8_STAGE(PG8_SB(1, 1), b3 + xhB, xB0, xB1);
;             PG8_WAIT_V(6); PG8_BAR; PG8_MMA(1, 1, At, B1); PG8_BAR;
	s_waitcnt lgkmcnt(0)
	s_setprio 1
	v_mfma_f32_16x16x32_bf16 v[116:119], v[218:221], v[186:189], v[116:119]
	v_mfma_f32_16x16x32_bf16 v[112:115], v[226:229], v[186:189], v[112:115]
	v_mfma_f32_16x16x32_bf16 v[92:95], v[218:221], v[194:197], v[92:95]
	v_mfma_f32_16x16x32_bf16 v[88:91], v[226:229], v[194:197], v[88:91]
	v_mfma_f32_16x16x32_bf16 v[76:79], v[218:221], v[202:205], v[76:79]
	v_mfma_f32_16x16x32_bf16 v[72:75], v[226:229], v[202:205], v[72:75]
	v_mfma_f32_16x16x32_bf16 v[68:71], v[218:221], v[210:213], v[68:71]
	v_mfma_f32_16x16x32_bf16 v[64:67], v[226:229], v[210:213], v[64:67]
	v_mfma_f32_16x16x32_bf16 v[116:119], v[222:225], v[190:193], v[116:119]
	v_mfma_f32_16x16x32_bf16 v[112:115], v[230:233], v[190:193], v[112:115]
	v_mfma_f32_16x16x32_bf16 v[92:95], v[222:225], v[198:201], v[92:95]
	v_mfma_f32_16x16x32_bf16 v[88:91], v[230:233], v[198:201], v[88:91]
	v_mfma_f32_16x16x32_bf16 v[76:79], v[222:225], v[206:209], v[76:79]
	v_mfma_f32_16x16x32_bf16 v[72:75], v[230:233], v[206:209], v[72:75]
	v_mfma_f32_16x16x32_bf16 v[68:71], v[222:225], v[214:217], v[68:71]
	v_mfma_f32_16x16x32_bf16 v[64:67], v[230:233], v[214:217], v[64:67]
	s_setprio 0
	s_mov_b32 m0, s65
	v_lshl_add_u64 v[138:139], v[234:235], 0, s[44:45]
	s_barrier
	ds_read_b128 v[186:189], v148 offset:49152
	ds_read_b128 v[190:193], v148 offset:50176
	ds_read_b128 v[194:197], v148 offset:51200
	ds_read_b128 v[198:201], v148 offset:52224
	ds_read_b128 v[202:205], v148 offset:53248
	ds_read_b128 v[206:209], v148 offset:54272
	ds_read_b128 v[210:213], v148 offset:55296
	ds_read_b128 v[214:217], v148 offset:56320
	global_load_lds_dwordx4 v[138:139], off
	v_lshl_add_u64 v[138:139], v[236:237], 0, s[44:45]
	s_mov_b32 m0, s66
	s_nop 0
	global_load_lds_dwordx4 v[138:139], off
	s_barrier
	s_waitcnt lgkmcnt(0)
	s_setprio 1
	v_mfma_f32_16x16x32_bf16 v[60:63], v[150:153], v[186:189], v[60:63]
	v_mfma_f32_16x16x32_bf16 v[56:59], v[158:161], v[186:189], v[56:59]
	v_mfma_f32_16x16x32_bf16 v[44:47], v[150:153], v[194:197], v[44:47]
	v_mfma_f32_16x16x32_bf16 v[40:43], v[158:161], v[194:197], v[40:43]
	v_mfma_f32_16x16x32_bf16 v[28:31], v[150:153], v[202:205], v[28:31]
	v_mfma_f32_16x16x32_bf16 v[24:27], v[158:161], v[202:205], v[24:27]
	v_mfma_f32_16x16x32_bf16 v[12:15], v[150:153], v[210:213], v[12:15]
	v_mfma_f32_16x16x32_bf16 v[8:11], v[158:161], v[210:213], v[8:11]
	v_mfma_f32_16x16x32_bf16 v[60:63], v[154:157], v[190:193], v[60:63]
	v_mfma_f32_16x16x32_bf16 v[56:59], v[182:185], v[190:193], v[56:59]
	v_mfma_f32_16x16x32_bf16 v[44:47], v[154:157], v[198:201], v[44:47]
	v_mfma_f32_16x16x32_bf16 v[40:43], v[182:185], v[198:201], v[40:43]
	v_mfma_f32_16x16x32_bf16 v[28:31], v[154:157], v[206:209], v[28:31]
	v_mfma_f32_16x16x32_bf16 v[24:27], v[182:185], v[206:209], v[24:27]
	v_mfma_f32_16x16x32_bf16 v[12:15], v[154:157], v[214:217], v[12:15]
	v_mfma_f32_16x16x32_bf16 v[8:11], v[182:185], v[214:217], v[8:11]
	s_setprio 0
	s_barrier
	s_add_u32 s34, s34, 0x200080
	s_addc_u32 s35, s35, 0
	s_add_i32 s15, s38, s48
	v_lshl_add_u64 v[138:139], s[34:35], 0, v[142:143]
	s_mov_b32 m0, s15
	v_lshl_add_u64 v[134:135], s[34:35], 0, v[134:135]
	global_load_lds_dwordx4 v[138:139], off
	s_add_i32 m0, s15, 0x2000
	s_nop 0
	global_load_lds_dwordx4 v[134:135], off
	s_waitcnt vmcnt(6)
	s_barrier
	s_setprio 1
	v_mfma_f32_16x16x32_bf16 v[52:55], v[218:221], v[186:189], v[52:55]
	v_mfma_f32_16x16x32_bf16 v[48:51], v[226:229], v[186:189], v[48:51]
	v_mfma_f32_16x16x32_bf16 v[36:39], v[218:221], v[194:197], v[36:39]
	v_mfma_f32_16x16x32_bf16 v[32:35], v[226:229], v[194:197], v[32:35]
	v_mfma_f32_16x16x32_bf16 v[20:23], v[218:221], v[202:205], v[20:23]
	v_mfma_f32_16x16x32_bf16 v[16:19], v[226:229], v[202:205], v[16:19]
	v_mfma_f32_16x16x32_bf16 v[4:7], v[218:221], v[210:213], v[4:7]
	v_mfma_f32_16x16x32_bf16 v[0:3], v[226:229], v[210:213], v[0:3]
	v_mfma_f32_16x16x32_bf16 v[52:55], v[222:225], v[190:193], v[52:55]
	v_mfma_f32_16x16x32_bf16 v[48:51], v[230:233], v[190:193], v[48:51]
	v_mfma_f32_16x16x32_bf16 v[36:39], v[222:225], v[198:201], v[36:39]
	v_mfma_f32_16x16x32_bf16 v[32:35], v[230:233], v[198:201], v[32:35]
	v_mfma_f32_16x16x32_bf16 v[20:23], v[222:225], v[206:209], v[20:23]
	v_mfma_f32_16x16x32_bf16 v[16:19], v[230:233], v[206:209], v[16:19]
	v_mfma_f32_16x16x32_bf16 v[4:7], v[222:225], v[214:217], v[4:7]
	v_mfma_f32_16x16x32_bf16 v[0:3], v[230:233], v[214:217], v[0:3]
	s_setprio 0
	s_add_i32 s11, s11, 2
	s_add_u32 s24, s24, 0x100
	s_addc_u32 s25, s25, 0
	s_add_u32 s26, s26, 0x100
	s_addc_u32 s27, s27, 0
	s_cmpk_gt_u32 s11, 0x7d
	s_cbranch_scc1 .Lrot_exit_4
	s_cmpk_eq_i32 s11, 0x7c
	s_cselect_b64 s[38:39], -1, 0
	s_and_b64 vcc, exec, s[38:39]
	v_mov_b64_e32 v[134:135], v[130:131]
	v_mov_b64_e32 v[142:143], v[128:129]
	s_mov_b64 s[34:35], s[22:23]
	s_cbranch_vccnz .Lrot_join_4
	v_mov_b64_e32 v[134:135], v[132:133]
	v_mov_b64_e32 v[142:143], v[136:137]
	s_mov_b64 s[34:35], s[26:27]
